# recurrence scalars through SMEM ring, next-chunk prefetch clamped to the stream (no out-of-stream scalar-cache lines)
# speedup vs baseline: 1.0384x; 1.0045x over previous
.LBB0_824:
	s_add_i32 s39, s14, 1
	s_and_saveexec_b64 s[24:25], s[44:45]
	s_xor_b64 s[24:25], exec, s[24:25]
	s_cbranch_execz .LBB0_826
	s_and_b32 s26, s39, 1
	s_mul_i32 s27, s26, 0xc200
	s_add_i32 s27, s27, 0
	v_add_u32_e32 v0, s27, v41
	v_add_u32_e32 v43, s27, v51
	v_mov_b32_e32 v53, s27
	v_lshl_add_u32 v54, s26, 11, v39
	v_add_u32_e32 v55, 0x400, v54
	s_lshl_b32 s96, s39, 9
	s_add_u32 s96, s100, s96
	s_addc_u32 s97, s101, 0
	ds_read_b128 v[56:59], v0 offset:4096
	ds_read_b128 v[60:63], v0 offset:4352
	ds_read_b128 v[64:67], v0 offset:5632
	ds_read_b128 v[68:71], v0 offset:5888
	ds_read2st64_b32 v[104:105], v43 offset0:20 offset1:26
	ds_read_b128 v[88:91], v0 offset:4608
	ds_read_b128 v[92:95], v0 offset:4864
	ds_read_b128 v[96:99], v0 offset:6144
	ds_read_b128 v[100:103], v0 offset:6400
	s_waitcnt lgkmcnt(0)
	s_load_dwordx8 s[28:35], s[96:97], 0x40
	v_mov_b32_e32 v108, s76
	v_pk_mul_f32 v[124:125], v[2:3], v[56:57]
	ds_read_b128 v[72:75], v0 offset:7168
	v_pk_mul_f32 v[126:127], v[2:3], v[88:89]
	ds_read_b128 v[76:79], v0 offset:7424
	v_pk_mul_f32 v[128:129], v[2:3], v[64:65]
	ds_read_b128 v[80:83], v0 offset:8704
	v_pk_mul_f32 v[134:135], v[2:3], v[96:97]
	ds_read_b128 v[84:87], v0 offset:8960
	v_pk_fma_f32 v[124:125], v[4:5], v[58:59], v[124:125]
	ds_read2st64_b32 v[106:107], v43 offset0:32 offset1:38
	v_pk_fma_f32 v[126:127], v[4:5], v[90:91], v[126:127]
	v_pk_fma_f32 v[128:129], v[4:5], v[66:67], v[128:129]
	v_pk_fma_f32 v[134:135], v[4:5], v[98:99], v[134:135]
	v_pk_fma_f32 v[124:125], v[6:7], v[60:61], v[124:125]
	v_pk_fma_f32 v[126:127], v[6:7], v[92:93], v[126:127]
	v_pk_fma_f32 v[128:129], v[6:7], v[68:69], v[128:129]
	v_pk_fma_f32 v[134:135], v[6:7], v[100:101], v[134:135]
	v_pk_fma_f32 v[124:125], v[8:9], v[62:63], v[124:125]
	v_pk_fma_f32 v[126:127], v[8:9], v[94:95], v[126:127]
	v_pk_fma_f32 v[128:129], v[8:9], v[70:71], v[128:129]
	v_pk_fma_f32 v[134:135], v[8:9], v[102:103], v[134:135]
	v_add_f32_e32 v124, v124, v125
	v_add_f32_e32 v126, v126, v127
	v_add_f32_e32 v128, v128, v129
	v_add_f32_e32 v134, v134, v135
	v_mul_f32_e32 v142, s80, v108
	v_add_f32_dpp v125, v124, v124 row_mirror row_mask:0xf bank_mask:0xf
	v_add_f32_dpp v125, v126, v126 row_mirror row_mask:0xf bank_mask:0xc
	v_add_f32_dpp v127, v128, v128 row_mirror row_mask:0xf bank_mask:0xf
	v_add_f32_dpp v127, v134, v134 row_mirror row_mask:0xf bank_mask:0xc
	v_add_f32_dpp v129, v125, v125 row_half_mirror row_mask:0xf bank_mask:0xf
	v_pk_mul_f32 v[2:3], v[2:3], v[142:143] op_sel_hi:[1,0]
	v_pk_mul_f32 v[4:5], v[4:5], v[142:143] op_sel_hi:[1,0]
	v_add_f32_dpp v129, v127, v127 row_half_mirror row_mask:0xf bank_mask:0xa
	v_pk_mul_f32 v[6:7], v[6:7], v[142:143] op_sel_hi:[1,0]
	v_pk_mul_f32 v[8:9], v[8:9], v[142:143] op_sel_hi:[1,0]
	v_add_f32_dpp v129, v129, v129 quad_perm:[1,0,3,2] row_mask:0xf bank_mask:0xf
	ds_read_b128 v[88:91], v0 offset:7680
	ds_read_b128 v[92:95], v0 offset:7936
	v_add_f32_dpp v129, v129, v129 quad_perm:[2,3,0,1] row_mask:0xf bank_mask:0xf
	ds_read_b128 v[96:99], v0 offset:9216
	ds_read_b128 v[100:103], v0 offset:9472
	v_fmac_f32_dpp v104, -v129, v108 row_newbcast:0 row_mask:0xf bank_mask:0xf
	v_mul_f32_dpp v141, v129, v108 row_newbcast:4 row_mask:0xf bank_mask:0xf
	v_mul_f32_e32 v138, s77, v104
	v_mul_f32_dpp v139, v129, v108 row_newbcast:8 row_mask:0xf bank_mask:0xf
	v_fmac_f32_e32 v141, s79, v138
	v_mul_f32_dpp v143, v129, v108 row_newbcast:12 row_mask:0xf bank_mask:0xf
	v_fma_f32 v105, -s80, v141, v105
	v_mul_f32_e32 v144, s80, v138
	v_mul_f32_e32 v140, s81, v105
	v_fmac_f32_e32 v139, s78, v138
	v_pk_fma_f32 v[2:3], v[56:57], v[144:145], v[2:3] op_sel_hi:[1,0,1]
	v_fmac_f32_e32 v143, s83, v138
	v_pk_fma_f32 v[4:5], v[58:59], v[144:145], v[4:5] op_sel_hi:[1,0,1]
	v_pk_fma_f32 v[6:7], v[60:61], v[144:145], v[6:7] op_sel_hi:[1,0,1]
	v_pk_fma_f32 v[8:9], v[62:63], v[144:145], v[8:9] op_sel_hi:[1,0,1]
	v_pk_fma_f32 v[2:3], v[64:65], v[140:141], v[2:3] op_sel_hi:[1,0,1]
	v_pk_fma_f32 v[4:5], v[66:67], v[140:141], v[4:5] op_sel_hi:[1,0,1]
	v_pk_fma_f32 v[6:7], v[68:69], v[140:141], v[6:7] op_sel_hi:[1,0,1]
	v_pk_fma_f32 v[8:9], v[70:71], v[140:141], v[8:9] op_sel_hi:[1,0,1]
	s_waitcnt lgkmcnt(0)
	s_load_dwordx8 s[4:11], s[96:97], 0x60
	v_mov_b32_e32 v108, s88
	v_pk_mul_f32 v[124:125], v[2:3], v[72:73]
	v_mul_f32_e32 v143, s80, v143
	v_pk_mul_f32 v[126:127], v[2:3], v[88:89]
	v_fmac_f32_e32 v143, s82, v140
	v_pk_mul_f32 v[128:129], v[2:3], v[80:81]
	ds_write2_b32 v54, v139, v143 offset0:0 offset1:16
	v_pk_mul_f32 v[134:135], v[2:3], v[96:97]
	ds_read_b128 v[56:59], v0 offset:10240
	v_pk_fma_f32 v[124:125], v[4:5], v[74:75], v[124:125]
	ds_read_b128 v[60:63], v0 offset:10496
	v_pk_fma_f32 v[126:127], v[4:5], v[90:91], v[126:127]
	ds_read_b128 v[64:67], v0 offset:11776
	v_pk_fma_f32 v[128:129], v[4:5], v[82:83], v[128:129]
	ds_read_b128 v[68:71], v0 offset:12032
	v_pk_fma_f32 v[134:135], v[4:5], v[98:99], v[134:135]
	ds_read2st64_b32 v[104:105], v43 offset0:44 offset1:50
	v_pk_fma_f32 v[124:125], v[6:7], v[76:77], v[124:125]
	v_pk_fma_f32 v[126:127], v[6:7], v[92:93], v[126:127]
	v_pk_fma_f32 v[128:129], v[6:7], v[84:85], v[128:129]
	v_pk_fma_f32 v[134:135], v[6:7], v[100:101], v[134:135]
	v_pk_fma_f32 v[124:125], v[8:9], v[78:79], v[124:125]
	v_pk_fma_f32 v[126:127], v[8:9], v[94:95], v[126:127]
	v_pk_fma_f32 v[128:129], v[8:9], v[86:87], v[128:129]
	v_pk_fma_f32 v[134:135], v[8:9], v[102:103], v[134:135]
	v_add_f32_e32 v124, v124, v125
	v_add_f32_e32 v126, v126, v127
	v_add_f32_e32 v128, v128, v129
	v_add_f32_e32 v134, v134, v135
	v_mul_f32_e32 v142, s92, v108
	v_add_f32_dpp v125, v124, v124 row_mirror row_mask:0xf bank_mask:0xf
	v_add_f32_dpp v125, v126, v126 row_mirror row_mask:0xf bank_mask:0xc
	v_add_f32_dpp v127, v128, v128 row_mirror row_mask:0xf bank_mask:0xf
	v_add_f32_dpp v127, v134, v134 row_mirror row_mask:0xf bank_mask:0xc
	v_add_f32_dpp v129, v125, v125 row_half_mirror row_mask:0xf bank_mask:0xf
	v_pk_mul_f32 v[2:3], v[2:3], v[142:143] op_sel_hi:[1,0]
	v_pk_mul_f32 v[4:5], v[4:5], v[142:143] op_sel_hi:[1,0]
	v_add_f32_dpp v129, v127, v127 row_half_mirror row_mask:0xf bank_mask:0xa
	v_pk_mul_f32 v[6:7], v[6:7], v[142:143] op_sel_hi:[1,0]
	v_pk_mul_f32 v[8:9], v[8:9], v[142:143] op_sel_hi:[1,0]
	v_add_f32_dpp v129, v129, v129 quad_perm:[1,0,3,2] row_mask:0xf bank_mask:0xf
	ds_read_b128 v[88:91], v0 offset:10752
	ds_read_b128 v[92:95], v0 offset:11008
	v_add_f32_dpp v129, v129, v129 quad_perm:[2,3,0,1] row_mask:0xf bank_mask:0xf
	ds_read_b128 v[96:99], v0 offset:12288
	ds_read_b128 v[100:103], v0 offset:12544
	v_fmac_f32_dpp v106, -v129, v108 row_newbcast:0 row_mask:0xf bank_mask:0xf
	v_mul_f32_dpp v141, v129, v108 row_newbcast:4 row_mask:0xf bank_mask:0xf
	v_mul_f32_e32 v138, s89, v106
	v_mul_f32_dpp v139, v129, v108 row_newbcast:8 row_mask:0xf bank_mask:0xf
	v_fmac_f32_e32 v141, s91, v138
	v_mul_f32_dpp v143, v129, v108 row_newbcast:12 row_mask:0xf bank_mask:0xf
	v_fma_f32 v107, -s92, v141, v107
	v_mul_f32_e32 v144, s92, v138
	v_mul_f32_e32 v140, s93, v107
	v_fmac_f32_e32 v139, s90, v138
	v_pk_fma_f32 v[2:3], v[72:73], v[144:145], v[2:3] op_sel_hi:[1,0,1]
	v_fmac_f32_e32 v143, s95, v138
	v_pk_fma_f32 v[4:5], v[74:75], v[144:145], v[4:5] op_sel_hi:[1,0,1]
	v_pk_fma_f32 v[6:7], v[76:77], v[144:145], v[6:7] op_sel_hi:[1,0,1]
	v_pk_fma_f32 v[8:9], v[78:79], v[144:145], v[8:9] op_sel_hi:[1,0,1]
	v_pk_fma_f32 v[2:3], v[80:81], v[140:141], v[2:3] op_sel_hi:[1,0,1]
	v_pk_fma_f32 v[4:5], v[82:83], v[140:141], v[4:5] op_sel_hi:[1,0,1]
	v_pk_fma_f32 v[6:7], v[84:85], v[140:141], v[6:7] op_sel_hi:[1,0,1]
	v_pk_fma_f32 v[8:9], v[86:87], v[140:141], v[8:9] op_sel_hi:[1,0,1]
	s_waitcnt lgkmcnt(0)
	s_load_dwordx8 s[76:83], s[96:97], 0x80
	v_mov_b32_e32 v108, s28
	v_pk_mul_f32 v[124:125], v[2:3], v[56:57]
	v_mul_f32_e32 v143, s92, v143
	v_pk_mul_f32 v[126:127], v[2:3], v[88:89]
	v_fmac_f32_e32 v143, s94, v140
	v_pk_mul_f32 v[128:129], v[2:3], v[64:65]
	ds_write2_b32 v54, v139, v143 offset0:32 offset1:48
	v_pk_mul_f32 v[134:135], v[2:3], v[96:97]
	ds_read_b128 v[72:75], v0 offset:13312
	v_pk_fma_f32 v[124:125], v[4:5], v[58:59], v[124:125]
	ds_read_b128 v[76:79], v0 offset:13568
	v_pk_fma_f32 v[126:127], v[4:5], v[90:91], v[126:127]
	ds_read_b128 v[80:83], v0 offset:14848
	v_pk_fma_f32 v[128:129], v[4:5], v[66:67], v[128:129]
	ds_read_b128 v[84:87], v0 offset:15104
	v_pk_fma_f32 v[134:135], v[4:5], v[98:99], v[134:135]
	ds_read2st64_b32 v[106:107], v43 offset0:56 offset1:62
	v_pk_fma_f32 v[124:125], v[6:7], v[60:61], v[124:125]
	v_pk_fma_f32 v[126:127], v[6:7], v[92:93], v[126:127]
	v_pk_fma_f32 v[128:129], v[6:7], v[68:69], v[128:129]
	v_pk_fma_f32 v[134:135], v[6:7], v[100:101], v[134:135]
	v_pk_fma_f32 v[124:125], v[8:9], v[62:63], v[124:125]
	v_pk_fma_f32 v[126:127], v[8:9], v[94:95], v[126:127]
	v_pk_fma_f32 v[128:129], v[8:9], v[70:71], v[128:129]
	v_pk_fma_f32 v[134:135], v[8:9], v[102:103], v[134:135]
	v_add_f32_e32 v124, v124, v125
	v_add_f32_e32 v126, v126, v127
	v_add_f32_e32 v128, v128, v129
	v_add_f32_e32 v134, v134, v135
	v_mul_f32_e32 v142, s32, v108
	v_add_f32_dpp v125, v124, v124 row_mirror row_mask:0xf bank_mask:0xf
	v_add_f32_dpp v125, v126, v126 row_mirror row_mask:0xf bank_mask:0xc
	v_add_f32_dpp v127, v128, v128 row_mirror row_mask:0xf bank_mask:0xf
	v_add_f32_dpp v127, v134, v134 row_mirror row_mask:0xf bank_mask:0xc
	v_add_f32_dpp v129, v125, v125 row_half_mirror row_mask:0xf bank_mask:0xf
	v_pk_mul_f32 v[2:3], v[2:3], v[142:143] op_sel_hi:[1,0]
	v_pk_mul_f32 v[4:5], v[4:5], v[142:143] op_sel_hi:[1,0]
	v_add_f32_dpp v129, v127, v127 row_half_mirror row_mask:0xf bank_mask:0xa
	v_pk_mul_f32 v[6:7], v[6:7], v[142:143] op_sel_hi:[1,0]
	v_pk_mul_f32 v[8:9], v[8:9], v[142:143] op_sel_hi:[1,0]
	v_add_f32_dpp v129, v129, v129 quad_perm:[1,0,3,2] row_mask:0xf bank_mask:0xf
	ds_read_b128 v[88:91], v0 offset:13824
	ds_read_b128 v[92:95], v0 offset:14080
	v_add_f32_dpp v129, v129, v129 quad_perm:[2,3,0,1] row_mask:0xf bank_mask:0xf
	ds_read_b128 v[96:99], v0 offset:15360
	ds_read_b128 v[100:103], v0 offset:15616
	v_fmac_f32_dpp v104, -v129, v108 row_newbcast:0 row_mask:0xf bank_mask:0xf
	v_mul_f32_dpp v141, v129, v108 row_newbcast:4 row_mask:0xf bank_mask:0xf
	v_mul_f32_e32 v138, s29, v104
	v_mul_f32_dpp v139, v129, v108 row_newbcast:8 row_mask:0xf bank_mask:0xf
	v_fmac_f32_e32 v141, s31, v138
	v_mul_f32_dpp v143, v129, v108 row_newbcast:12 row_mask:0xf bank_mask:0xf
	v_fma_f32 v105, -s32, v141, v105
	v_mul_f32_e32 v144, s32, v138
	v_mul_f32_e32 v140, s33, v105
	v_fmac_f32_e32 v139, s30, v138
	v_pk_fma_f32 v[2:3], v[56:57], v[144:145], v[2:3] op_sel_hi:[1,0,1]
	v_fmac_f32_e32 v143, s35, v138
	v_pk_fma_f32 v[4:5], v[58:59], v[144:145], v[4:5] op_sel_hi:[1,0,1]
	v_pk_fma_f32 v[6:7], v[60:61], v[144:145], v[6:7] op_sel_hi:[1,0,1]
	v_pk_fma_f32 v[8:9], v[62:63], v[144:145], v[8:9] op_sel_hi:[1,0,1]
	v_pk_fma_f32 v[2:3], v[64:65], v[140:141], v[2:3] op_sel_hi:[1,0,1]
	v_pk_fma_f32 v[4:5], v[66:67], v[140:141], v[4:5] op_sel_hi:[1,0,1]
	v_pk_fma_f32 v[6:7], v[68:69], v[140:141], v[6:7] op_sel_hi:[1,0,1]
	v_pk_fma_f32 v[8:9], v[70:71], v[140:141], v[8:9] op_sel_hi:[1,0,1]
	s_waitcnt lgkmcnt(0)
	s_load_dwordx8 s[88:95], s[96:97], 0xa0
	v_mov_b32_e32 v108, s4
	v_pk_mul_f32 v[124:125], v[2:3], v[72:73]
	v_mul_f32_e32 v143, s32, v143
	v_pk_mul_f32 v[126:127], v[2:3], v[88:89]
	v_fmac_f32_e32 v143, s34, v140
	v_pk_mul_f32 v[128:129], v[2:3], v[80:81]
	ds_write2_b32 v54, v139, v143 offset0:64 offset1:80
	v_pk_mul_f32 v[134:135], v[2:3], v[96:97]
	ds_read_b128 v[56:59], v0 offset:16384
	v_pk_fma_f32 v[124:125], v[4:5], v[74:75], v[124:125]
	ds_read_b128 v[60:63], v0 offset:16640
	v_pk_fma_f32 v[126:127], v[4:5], v[90:91], v[126:127]
	ds_read_b128 v[64:67], v0 offset:17920
	v_pk_fma_f32 v[128:129], v[4:5], v[82:83], v[128:129]
	ds_read_b128 v[68:71], v0 offset:18176
	v_pk_fma_f32 v[134:135], v[4:5], v[98:99], v[134:135]
	ds_read2st64_b32 v[104:105], v43 offset0:68 offset1:74
	v_pk_fma_f32 v[124:125], v[6:7], v[76:77], v[124:125]
	v_pk_fma_f32 v[126:127], v[6:7], v[92:93], v[126:127]
	v_pk_fma_f32 v[128:129], v[6:7], v[84:85], v[128:129]
	v_pk_fma_f32 v[134:135], v[6:7], v[100:101], v[134:135]
	v_pk_fma_f32 v[124:125], v[8:9], v[78:79], v[124:125]
	v_pk_fma_f32 v[126:127], v[8:9], v[94:95], v[126:127]
	v_pk_fma_f32 v[128:129], v[8:9], v[86:87], v[128:129]
	v_pk_fma_f32 v[134:135], v[8:9], v[102:103], v[134:135]
	v_add_f32_e32 v124, v124, v125
	v_add_f32_e32 v126, v126, v127
	v_add_f32_e32 v128, v128, v129
	v_add_f32_e32 v134, v134, v135
	v_mul_f32_e32 v142, s8, v108
	v_add_f32_dpp v125, v124, v124 row_mirror row_mask:0xf bank_mask:0xf
	v_add_f32_dpp v125, v126, v126 row_mirror row_mask:0xf bank_mask:0xc
	v_add_f32_dpp v127, v128, v128 row_mirror row_mask:0xf bank_mask:0xf
	v_add_f32_dpp v127, v134, v134 row_mirror row_mask:0xf bank_mask:0xc
	v_add_f32_dpp v129, v125, v125 row_half_mirror row_mask:0xf bank_mask:0xf
	v_pk_mul_f32 v[2:3], v[2:3], v[142:143] op_sel_hi:[1,0]
	v_pk_mul_f32 v[4:5], v[4:5], v[142:143] op_sel_hi:[1,0]
	v_add_f32_dpp v129, v127, v127 row_half_mirror row_mask:0xf bank_mask:0xa
	v_pk_mul_f32 v[6:7], v[6:7], v[142:143] op_sel_hi:[1,0]
	v_pk_mul_f32 v[8:9], v[8:9], v[142:143] op_sel_hi:[1,0]
	v_add_f32_dpp v129, v129, v129 quad_perm:[1,0,3,2] row_mask:0xf bank_mask:0xf
	ds_read_b128 v[88:91], v0 offset:16896
	ds_read_b128 v[92:95], v0 offset:17152
	v_add_f32_dpp v129, v129, v129 quad_perm:[2,3,0,1] row_mask:0xf bank_mask:0xf
	ds_read_b128 v[96:99], v0 offset:18432
	ds_read_b128 v[100:103], v0 offset:18688
	v_fmac_f32_dpp v106, -v129, v108 row_newbcast:0 row_mask:0xf bank_mask:0xf
	v_mul_f32_dpp v141, v129, v108 row_newbcast:4 row_mask:0xf bank_mask:0xf
	v_mul_f32_e32 v138, s5, v106
	v_mul_f32_dpp v139, v129, v108 row_newbcast:8 row_mask:0xf bank_mask:0xf
	v_fmac_f32_e32 v141, s7, v138
	v_mul_f32_dpp v143, v129, v108 row_newbcast:12 row_mask:0xf bank_mask:0xf
	v_fma_f32 v107, -s8, v141, v107
	v_mul_f32_e32 v144, s8, v138
	v_mul_f32_e32 v140, s9, v107
	v_fmac_f32_e32 v139, s6, v138
	v_pk_fma_f32 v[2:3], v[72:73], v[144:145], v[2:3] op_sel_hi:[1,0,1]
	v_fmac_f32_e32 v143, s11, v138
	v_pk_fma_f32 v[4:5], v[74:75], v[144:145], v[4:5] op_sel_hi:[1,0,1]
	v_pk_fma_f32 v[6:7], v[76:77], v[144:145], v[6:7] op_sel_hi:[1,0,1]
	v_pk_fma_f32 v[8:9], v[78:79], v[144:145], v[8:9] op_sel_hi:[1,0,1]
	v_pk_fma_f32 v[2:3], v[80:81], v[140:141], v[2:3] op_sel_hi:[1,0,1]
	v_pk_fma_f32 v[4:5], v[82:83], v[140:141], v[4:5] op_sel_hi:[1,0,1]
	v_pk_fma_f32 v[6:7], v[84:85], v[140:141], v[6:7] op_sel_hi:[1,0,1]
	v_pk_fma_f32 v[8:9], v[86:87], v[140:141], v[8:9] op_sel_hi:[1,0,1]
	s_waitcnt lgkmcnt(0)
	s_load_dwordx8 s[28:35], s[96:97], 0xc0
	v_mov_b32_e32 v108, s76
	v_pk_mul_f32 v[124:125], v[2:3], v[56:57]
	v_mul_f32_e32 v143, s8, v143
	v_pk_mul_f32 v[126:127], v[2:3], v[88:89]
	v_fmac_f32_e32 v143, s10, v140
	v_pk_mul_f32 v[128:129], v[2:3], v[64:65]
	ds_write2_b32 v54, v139, v143 offset0:96 offset1:112
	v_pk_mul_f32 v[134:135], v[2:3], v[96:97]
	ds_read_b128 v[72:75], v0 offset:19456
	v_pk_fma_f32 v[124:125], v[4:5], v[58:59], v[124:125]
	ds_read_b128 v[76:79], v0 offset:19712
	v_pk_fma_f32 v[126:127], v[4:5], v[90:91], v[126:127]
	ds_read_b128 v[80:83], v0 offset:20992
	v_pk_fma_f32 v[128:129], v[4:5], v[66:67], v[128:129]
	ds_read_b128 v[84:87], v0 offset:21248
	v_pk_fma_f32 v[134:135], v[4:5], v[98:99], v[134:135]
	ds_read2st64_b32 v[106:107], v43 offset0:80 offset1:86
	v_pk_fma_f32 v[124:125], v[6:7], v[60:61], v[124:125]
	v_pk_fma_f32 v[126:127], v[6:7], v[92:93], v[126:127]
	v_pk_fma_f32 v[128:129], v[6:7], v[68:69], v[128:129]
	v_pk_fma_f32 v[134:135], v[6:7], v[100:101], v[134:135]
	v_pk_fma_f32 v[124:125], v[8:9], v[62:63], v[124:125]
	v_pk_fma_f32 v[126:127], v[8:9], v[94:95], v[126:127]
	v_pk_fma_f32 v[128:129], v[8:9], v[70:71], v[128:129]
	v_pk_fma_f32 v[134:135], v[8:9], v[102:103], v[134:135]
	v_add_f32_e32 v124, v124, v125
	v_add_f32_e32 v126, v126, v127
	v_add_f32_e32 v128, v128, v129
	v_add_f32_e32 v134, v134, v135
	v_mul_f32_e32 v142, s80, v108
	v_add_f32_dpp v125, v124, v124 row_mirror row_mask:0xf bank_mask:0xf
	v_add_f32_dpp v125, v126, v126 row_mirror row_mask:0xf bank_mask:0xc
	v_add_f32_dpp v127, v128, v128 row_mirror row_mask:0xf bank_mask:0xf
	v_add_f32_dpp v127, v134, v134 row_mirror row_mask:0xf bank_mask:0xc
	v_add_f32_dpp v129, v125, v125 row_half_mirror row_mask:0xf bank_mask:0xf
	v_pk_mul_f32 v[2:3], v[2:3], v[142:143] op_sel_hi:[1,0]
	v_pk_mul_f32 v[4:5], v[4:5], v[142:143] op_sel_hi:[1,0]
	v_add_f32_dpp v129, v127, v127 row_half_mirror row_mask:0xf bank_mask:0xa
	v_pk_mul_f32 v[6:7], v[6:7], v[142:143] op_sel_hi:[1,0]
	v_pk_mul_f32 v[8:9], v[8:9], v[142:143] op_sel_hi:[1,0]
	v_add_f32_dpp v129, v129, v129 quad_perm:[1,0,3,2] row_mask:0xf bank_mask:0xf
	ds_read_b128 v[88:91], v0 offset:19968
	ds_read_b128 v[92:95], v0 offset:20224
	v_add_f32_dpp v129, v129, v129 quad_perm:[2,3,0,1] row_mask:0xf bank_mask:0xf
	ds_read_b128 v[96:99], v0 offset:21504
	ds_read_b128 v[100:103], v0 offset:21760
	v_fmac_f32_dpp v104, -v129, v108 row_newbcast:0 row_mask:0xf bank_mask:0xf
	v_mul_f32_dpp v141, v129, v108 row_newbcast:4 row_mask:0xf bank_mask:0xf
	v_mul_f32_e32 v138, s77, v104
	v_mul_f32_dpp v139, v129, v108 row_newbcast:8 row_mask:0xf bank_mask:0xf
	v_fmac_f32_e32 v141, s79, v138
	v_mul_f32_dpp v143, v129, v108 row_newbcast:12 row_mask:0xf bank_mask:0xf
	v_fma_f32 v105, -s80, v141, v105
	v_mul_f32_e32 v144, s80, v138
	v_mul_f32_e32 v140, s81, v105
	v_fmac_f32_e32 v139, s78, v138
	v_pk_fma_f32 v[2:3], v[56:57], v[144:145], v[2:3] op_sel_hi:[1,0,1]
	v_fmac_f32_e32 v143, s83, v138
	v_pk_fma_f32 v[4:5], v[58:59], v[144:145], v[4:5] op_sel_hi:[1,0,1]
	v_pk_fma_f32 v[6:7], v[60:61], v[144:145], v[6:7] op_sel_hi:[1,0,1]
	v_pk_fma_f32 v[8:9], v[62:63], v[144:145], v[8:9] op_sel_hi:[1,0,1]
	v_pk_fma_f32 v[2:3], v[64:65], v[140:141], v[2:3] op_sel_hi:[1,0,1]
	v_pk_fma_f32 v[4:5], v[66:67], v[140:141], v[4:5] op_sel_hi:[1,0,1]
	v_pk_fma_f32 v[6:7], v[68:69], v[140:141], v[6:7] op_sel_hi:[1,0,1]
	v_pk_fma_f32 v[8:9], v[70:71], v[140:141], v[8:9] op_sel_hi:[1,0,1]
	s_waitcnt lgkmcnt(0)
	s_load_dwordx8 s[4:11], s[96:97], 0xe0
	v_mov_b32_e32 v108, s88
	v_pk_mul_f32 v[124:125], v[2:3], v[72:73]
	v_mul_f32_e32 v143, s80, v143
	v_pk_mul_f32 v[126:127], v[2:3], v[88:89]
	v_fmac_f32_e32 v143, s82, v140
	v_pk_mul_f32 v[128:129], v[2:3], v[80:81]
	ds_write2_b32 v54, v139, v143 offset0:128 offset1:144
	v_pk_mul_f32 v[134:135], v[2:3], v[96:97]
	ds_read_b128 v[56:59], v0 offset:22528
	v_pk_fma_f32 v[124:125], v[4:5], v[74:75], v[124:125]
	ds_read_b128 v[60:63], v0 offset:22784
	v_pk_fma_f32 v[126:127], v[4:5], v[90:91], v[126:127]
	ds_read_b128 v[64:67], v0 offset:24064
	v_pk_fma_f32 v[128:129], v[4:5], v[82:83], v[128:129]
	ds_read_b128 v[68:71], v0 offset:24320
	v_pk_fma_f32 v[134:135], v[4:5], v[98:99], v[134:135]
	ds_read2st64_b32 v[104:105], v43 offset0:92 offset1:98
	v_pk_fma_f32 v[124:125], v[6:7], v[76:77], v[124:125]
	v_pk_fma_f32 v[126:127], v[6:7], v[92:93], v[126:127]
	v_pk_fma_f32 v[128:129], v[6:7], v[84:85], v[128:129]
	v_pk_fma_f32 v[134:135], v[6:7], v[100:101], v[134:135]
	v_pk_fma_f32 v[124:125], v[8:9], v[78:79], v[124:125]
	v_pk_fma_f32 v[126:127], v[8:9], v[94:95], v[126:127]
	v_pk_fma_f32 v[128:129], v[8:9], v[86:87], v[128:129]
	v_pk_fma_f32 v[134:135], v[8:9], v[102:103], v[134:135]
	v_add_f32_e32 v124, v124, v125
	v_add_f32_e32 v126, v126, v127
	v_add_f32_e32 v128, v128, v129
	v_add_f32_e32 v134, v134, v135
	v_mul_f32_e32 v142, s92, v108
	v_add_f32_dpp v125, v124, v124 row_mirror row_mask:0xf bank_mask:0xf
	v_add_f32_dpp v125, v126, v126 row_mirror row_mask:0xf bank_mask:0xc
	v_add_f32_dpp v127, v128, v128 row_mirror row_mask:0xf bank_mask:0xf
	v_add_f32_dpp v127, v134, v134 row_mirror row_mask:0xf bank_mask:0xc
	v_add_f32_dpp v129, v125, v125 row_half_mirror row_mask:0xf bank_mask:0xf
	v_pk_mul_f32 v[2:3], v[2:3], v[142:143] op_sel_hi:[1,0]
	v_pk_mul_f32 v[4:5], v[4:5], v[142:143] op_sel_hi:[1,0]
	v_add_f32_dpp v129, v127, v127 row_half_mirror row_mask:0xf bank_mask:0xa
	v_pk_mul_f32 v[6:7], v[6:7], v[142:143] op_sel_hi:[1,0]
	v_pk_mul_f32 v[8:9], v[8:9], v[142:143] op_sel_hi:[1,0]
	v_add_f32_dpp v129, v129, v129 quad_perm:[1,0,3,2] row_mask:0xf bank_mask:0xf
	ds_read_b128 v[88:91], v0 offset:23040
	ds_read_b128 v[92:95], v0 offset:23296
	v_add_f32_dpp v129, v129, v129 quad_perm:[2,3,0,1] row_mask:0xf bank_mask:0xf
	ds_read_b128 v[96:99], v0 offset:24576
	ds_read_b128 v[100:103], v0 offset:24832
	v_fmac_f32_dpp v106, -v129, v108 row_newbcast:0 row_mask:0xf bank_mask:0xf
	v_mul_f32_dpp v141, v129, v108 row_newbcast:4 row_mask:0xf bank_mask:0xf
	v_mul_f32_e32 v138, s89, v106
	v_mul_f32_dpp v139, v129, v108 row_newbcast:8 row_mask:0xf bank_mask:0xf
	v_fmac_f32_e32 v141, s91, v138
	v_mul_f32_dpp v143, v129, v108 row_newbcast:12 row_mask:0xf bank_mask:0xf
	v_fma_f32 v107, -s92, v141, v107
	v_mul_f32_e32 v144, s92, v138
	v_mul_f32_e32 v140, s93, v107
	v_fmac_f32_e32 v139, s90, v138
	v_pk_fma_f32 v[2:3], v[72:73], v[144:145], v[2:3] op_sel_hi:[1,0,1]
	v_fmac_f32_e32 v143, s95, v138
	v_pk_fma_f32 v[4:5], v[74:75], v[144:145], v[4:5] op_sel_hi:[1,0,1]
	v_pk_fma_f32 v[6:7], v[76:77], v[144:145], v[6:7] op_sel_hi:[1,0,1]
	v_pk_fma_f32 v[8:9], v[78:79], v[144:145], v[8:9] op_sel_hi:[1,0,1]
	v_pk_fma_f32 v[2:3], v[80:81], v[140:141], v[2:3] op_sel_hi:[1,0,1]
	v_pk_fma_f32 v[4:5], v[82:83], v[140:141], v[4:5] op_sel_hi:[1,0,1]
	v_pk_fma_f32 v[6:7], v[84:85], v[140:141], v[6:7] op_sel_hi:[1,0,1]
	v_pk_fma_f32 v[8:9], v[86:87], v[140:141], v[8:9] op_sel_hi:[1,0,1]
	s_waitcnt lgkmcnt(0)
	s_load_dwordx8 s[76:83], s[96:97], 0x100
	v_mov_b32_e32 v108, s28
	v_pk_mul_f32 v[124:125], v[2:3], v[56:57]
	v_mul_f32_e32 v143, s92, v143
	v_pk_mul_f32 v[126:127], v[2:3], v[88:89]
	v_fmac_f32_e32 v143, s94, v140
	v_pk_mul_f32 v[128:129], v[2:3], v[64:65]
	ds_write2_b32 v54, v139, v143 offset0:160 offset1:176
	v_pk_mul_f32 v[134:135], v[2:3], v[96:97]
	ds_read_b128 v[72:75], v0 offset:25600
	v_pk_fma_f32 v[124:125], v[4:5], v[58:59], v[124:125]
	ds_read_b128 v[76:79], v0 offset:25856
	v_pk_fma_f32 v[126:127], v[4:5], v[90:91], v[126:127]
	ds_read_b128 v[80:83], v0 offset:27136
	v_pk_fma_f32 v[128:129], v[4:5], v[66:67], v[128:129]
	ds_read_b128 v[84:87], v0 offset:27392
	v_pk_fma_f32 v[134:135], v[4:5], v[98:99], v[134:135]
	ds_read2st64_b32 v[106:107], v43 offset0:104 offset1:110
	v_pk_fma_f32 v[124:125], v[6:7], v[60:61], v[124:125]
	v_pk_fma_f32 v[126:127], v[6:7], v[92:93], v[126:127]
	v_pk_fma_f32 v[128:129], v[6:7], v[68:69], v[128:129]
	v_pk_fma_f32 v[134:135], v[6:7], v[100:101], v[134:135]
	v_pk_fma_f32 v[124:125], v[8:9], v[62:63], v[124:125]
	v_pk_fma_f32 v[126:127], v[8:9], v[94:95], v[126:127]
	v_pk_fma_f32 v[128:129], v[8:9], v[70:71], v[128:129]
	v_pk_fma_f32 v[134:135], v[8:9], v[102:103], v[134:135]
	v_add_f32_e32 v124, v124, v125
	v_add_f32_e32 v126, v126, v127
	v_add_f32_e32 v128, v128, v129
	v_add_f32_e32 v134, v134, v135
	v_mul_f32_e32 v142, s32, v108
	v_add_f32_dpp v125, v124, v124 row_mirror row_mask:0xf bank_mask:0xf
	v_add_f32_dpp v125, v126, v126 row_mirror row_mask:0xf bank_mask:0xc
	v_add_f32_dpp v127, v128, v128 row_mirror row_mask:0xf bank_mask:0xf
	v_add_f32_dpp v127, v134, v134 row_mirror row_mask:0xf bank_mask:0xc
	v_add_f32_dpp v129, v125, v125 row_half_mirror row_mask:0xf bank_mask:0xf
	v_pk_mul_f32 v[2:3], v[2:3], v[142:143] op_sel_hi:[1,0]
	v_pk_mul_f32 v[4:5], v[4:5], v[142:143] op_sel_hi:[1,0]
	v_add_f32_dpp v129, v127, v127 row_half_mirror row_mask:0xf bank_mask:0xa
	v_pk_mul_f32 v[6:7], v[6:7], v[142:143] op_sel_hi:[1,0]
	v_pk_mul_f32 v[8:9], v[8:9], v[142:143] op_sel_hi:[1,0]
	v_add_f32_dpp v129, v129, v129 quad_perm:[1,0,3,2] row_mask:0xf bank_mask:0xf
	ds_read_b128 v[88:91], v0 offset:26112
	ds_read_b128 v[92:95], v0 offset:26368
	v_add_f32_dpp v129, v129, v129 quad_perm:[2,3,0,1] row_mask:0xf bank_mask:0xf
	ds_read_b128 v[96:99], v0 offset:27648
	ds_read_b128 v[100:103], v0 offset:27904
	v_fmac_f32_dpp v104, -v129, v108 row_newbcast:0 row_mask:0xf bank_mask:0xf
	v_mul_f32_dpp v141, v129, v108 row_newbcast:4 row_mask:0xf bank_mask:0xf
	v_mul_f32_e32 v138, s29, v104
	v_mul_f32_dpp v139, v129, v108 row_newbcast:8 row_mask:0xf bank_mask:0xf
	v_fmac_f32_e32 v141, s31, v138
	v_mul_f32_dpp v143, v129, v108 row_newbcast:12 row_mask:0xf bank_mask:0xf
	v_fma_f32 v105, -s32, v141, v105
	v_mul_f32_e32 v144, s32, v138
	v_mul_f32_e32 v140, s33, v105
	v_fmac_f32_e32 v139, s30, v138
	v_pk_fma_f32 v[2:3], v[56:57], v[144:145], v[2:3] op_sel_hi:[1,0,1]
	v_fmac_f32_e32 v143, s35, v138
	v_pk_fma_f32 v[4:5], v[58:59], v[144:145], v[4:5] op_sel_hi:[1,0,1]
	v_pk_fma_f32 v[6:7], v[60:61], v[144:145], v[6:7] op_sel_hi:[1,0,1]
	v_pk_fma_f32 v[8:9], v[62:63], v[144:145], v[8:9] op_sel_hi:[1,0,1]
	v_pk_fma_f32 v[2:3], v[64:65], v[140:141], v[2:3] op_sel_hi:[1,0,1]
	v_pk_fma_f32 v[4:5], v[66:67], v[140:141], v[4:5] op_sel_hi:[1,0,1]
	v_pk_fma_f32 v[6:7], v[68:69], v[140:141], v[6:7] op_sel_hi:[1,0,1]
	v_pk_fma_f32 v[8:9], v[70:71], v[140:141], v[8:9] op_sel_hi:[1,0,1]
	s_waitcnt lgkmcnt(0)
	s_load_dwordx8 s[88:95], s[96:97], 0x120
	v_mov_b32_e32 v108, s4
	v_pk_mul_f32 v[124:125], v[2:3], v[72:73]
	v_mul_f32_e32 v143, s32, v143
	v_pk_mul_f32 v[126:127], v[2:3], v[88:89]
	v_fmac_f32_e32 v143, s34, v140
	v_pk_mul_f32 v[128:129], v[2:3], v[80:81]
	ds_write2_b32 v54, v139, v143 offset0:192 offset1:208
	v_pk_mul_f32 v[134:135], v[2:3], v[96:97]
	ds_read_b128 v[56:59], v0 offset:28672
	v_pk_fma_f32 v[124:125], v[4:5], v[74:75], v[124:125]
	ds_read_b128 v[60:63], v0 offset:28928
	v_pk_fma_f32 v[126:127], v[4:5], v[90:91], v[126:127]
	ds_read_b128 v[64:67], v0 offset:30208
	v_pk_fma_f32 v[128:129], v[4:5], v[82:83], v[128:129]
	ds_read_b128 v[68:71], v0 offset:30464
	v_pk_fma_f32 v[134:135], v[4:5], v[98:99], v[134:135]
	ds_read2st64_b32 v[104:105], v43 offset0:116 offset1:122
	v_pk_fma_f32 v[124:125], v[6:7], v[76:77], v[124:125]
	v_pk_fma_f32 v[126:127], v[6:7], v[92:93], v[126:127]
	v_pk_fma_f32 v[128:129], v[6:7], v[84:85], v[128:129]
	v_pk_fma_f32 v[134:135], v[6:7], v[100:101], v[134:135]
	v_pk_fma_f32 v[124:125], v[8:9], v[78:79], v[124:125]
	v_pk_fma_f32 v[126:127], v[8:9], v[94:95], v[126:127]
	v_pk_fma_f32 v[128:129], v[8:9], v[86:87], v[128:129]
	v_pk_fma_f32 v[134:135], v[8:9], v[102:103], v[134:135]
	v_add_f32_e32 v124, v124, v125
	v_add_f32_e32 v126, v126, v127
	v_add_f32_e32 v128, v128, v129
	v_add_f32_e32 v134, v134, v135
	v_mul_f32_e32 v142, s8, v108
	v_add_f32_dpp v125, v124, v124 row_mirror row_mask:0xf bank_mask:0xf
	v_add_f32_dpp v125, v126, v126 row_mirror row_mask:0xf bank_mask:0xc
	v_add_f32_dpp v127, v128, v128 row_mirror row_mask:0xf bank_mask:0xf
	v_add_f32_dpp v127, v134, v134 row_mirror row_mask:0xf bank_mask:0xc
	v_add_f32_dpp v129, v125, v125 row_half_mirror row_mask:0xf bank_mask:0xf
	v_pk_mul_f32 v[2:3], v[2:3], v[142:143] op_sel_hi:[1,0]
	v_pk_mul_f32 v[4:5], v[4:5], v[142:143] op_sel_hi:[1,0]
	v_add_f32_dpp v129, v127, v127 row_half_mirror row_mask:0xf bank_mask:0xa
	v_pk_mul_f32 v[6:7], v[6:7], v[142:143] op_sel_hi:[1,0]
	v_pk_mul_f32 v[8:9], v[8:9], v[142:143] op_sel_hi:[1,0]
	v_add_f32_dpp v129, v129, v129 quad_perm:[1,0,3,2] row_mask:0xf bank_mask:0xf
	ds_read_b128 v[88:91], v0 offset:29184
	ds_read_b128 v[92:95], v0 offset:29440
	v_add_f32_dpp v129, v129, v129 quad_perm:[2,3,0,1] row_mask:0xf bank_mask:0xf
	ds_read_b128 v[96:99], v0 offset:30720
	ds_read_b128 v[100:103], v0 offset:30976
	v_fmac_f32_dpp v106, -v129, v108 row_newbcast:0 row_mask:0xf bank_mask:0xf
	v_mul_f32_dpp v141, v129, v108 row_newbcast:4 row_mask:0xf bank_mask:0xf
	v_mul_f32_e32 v138, s5, v106
	v_mul_f32_dpp v139, v129, v108 row_newbcast:8 row_mask:0xf bank_mask:0xf
	v_fmac_f32_e32 v141, s7, v138
	v_mul_f32_dpp v143, v129, v108 row_newbcast:12 row_mask:0xf bank_mask:0xf
	v_fma_f32 v107, -s8, v141, v107
	v_mul_f32_e32 v144, s8, v138
	v_mul_f32_e32 v140, s9, v107
	v_fmac_f32_e32 v139, s6, v138
	v_pk_fma_f32 v[2:3], v[72:73], v[144:145], v[2:3] op_sel_hi:[1,0,1]
	v_fmac_f32_e32 v143, s11, v138
	v_pk_fma_f32 v[4:5], v[74:75], v[144:145], v[4:5] op_sel_hi:[1,0,1]
	v_pk_fma_f32 v[6:7], v[76:77], v[144:145], v[6:7] op_sel_hi:[1,0,1]
	v_pk_fma_f32 v[8:9], v[78:79], v[144:145], v[8:9] op_sel_hi:[1,0,1]
	v_pk_fma_f32 v[2:3], v[80:81], v[140:141], v[2:3] op_sel_hi:[1,0,1]
	v_pk_fma_f32 v[4:5], v[82:83], v[140:141], v[4:5] op_sel_hi:[1,0,1]
	v_pk_fma_f32 v[6:7], v[84:85], v[140:141], v[6:7] op_sel_hi:[1,0,1]
	v_pk_fma_f32 v[8:9], v[86:87], v[140:141], v[8:9] op_sel_hi:[1,0,1]
	s_waitcnt lgkmcnt(0)
	s_load_dwordx8 s[28:35], s[96:97], 0x140
	v_mov_b32_e32 v108, s76
	v_pk_mul_f32 v[124:125], v[2:3], v[56:57]
	v_mul_f32_e32 v143, s8, v143
	v_pk_mul_f32 v[126:127], v[2:3], v[88:89]
	v_fmac_f32_e32 v143, s10, v140
	v_pk_mul_f32 v[128:129], v[2:3], v[64:65]
	ds_write2_b32 v54, v139, v143 offset0:224 offset1:240
	v_pk_mul_f32 v[134:135], v[2:3], v[96:97]
	ds_read_b128 v[72:75], v0 offset:31744
	v_pk_fma_f32 v[124:125], v[4:5], v[58:59], v[124:125]
	ds_read_b128 v[76:79], v0 offset:32000
	v_pk_fma_f32 v[126:127], v[4:5], v[90:91], v[126:127]
	ds_read_b128 v[80:83], v0 offset:33280
	v_pk_fma_f32 v[128:129], v[4:5], v[66:67], v[128:129]
	ds_read_b128 v[84:87], v0 offset:33536
	v_pk_fma_f32 v[134:135], v[4:5], v[98:99], v[134:135]
	ds_read2st64_b32 v[106:107], v43 offset0:128 offset1:134
	v_pk_fma_f32 v[124:125], v[6:7], v[60:61], v[124:125]
	v_pk_fma_f32 v[126:127], v[6:7], v[92:93], v[126:127]
	v_pk_fma_f32 v[128:129], v[6:7], v[68:69], v[128:129]
	v_pk_fma_f32 v[134:135], v[6:7], v[100:101], v[134:135]
	v_pk_fma_f32 v[124:125], v[8:9], v[62:63], v[124:125]
	v_pk_fma_f32 v[126:127], v[8:9], v[94:95], v[126:127]
	v_pk_fma_f32 v[128:129], v[8:9], v[70:71], v[128:129]
	v_pk_fma_f32 v[134:135], v[8:9], v[102:103], v[134:135]
	v_add_f32_e32 v124, v124, v125
	v_add_f32_e32 v126, v126, v127
	v_add_f32_e32 v128, v128, v129
	v_add_f32_e32 v134, v134, v135
	v_mul_f32_e32 v142, s80, v108
	v_add_f32_dpp v125, v124, v124 row_mirror row_mask:0xf bank_mask:0xf
	v_add_f32_dpp v125, v126, v126 row_mirror row_mask:0xf bank_mask:0xc
	v_add_f32_dpp v127, v128, v128 row_mirror row_mask:0xf bank_mask:0xf
	v_add_f32_dpp v127, v134, v134 row_mirror row_mask:0xf bank_mask:0xc
	v_add_f32_dpp v129, v125, v125 row_half_mirror row_mask:0xf bank_mask:0xf
	v_pk_mul_f32 v[2:3], v[2:3], v[142:143] op_sel_hi:[1,0]
	v_pk_mul_f32 v[4:5], v[4:5], v[142:143] op_sel_hi:[1,0]
	v_add_f32_dpp v129, v127, v127 row_half_mirror row_mask:0xf bank_mask:0xa
	v_pk_mul_f32 v[6:7], v[6:7], v[142:143] op_sel_hi:[1,0]
	v_pk_mul_f32 v[8:9], v[8:9], v[142:143] op_sel_hi:[1,0]
	v_add_f32_dpp v129, v129, v129 quad_perm:[1,0,3,2] row_mask:0xf bank_mask:0xf
	ds_read_b128 v[88:91], v0 offset:32256
	ds_read_b128 v[92:95], v0 offset:32512
	v_add_f32_dpp v129, v129, v129 quad_perm:[2,3,0,1] row_mask:0xf bank_mask:0xf
	ds_read_b128 v[96:99], v0 offset:33792
	ds_read_b128 v[100:103], v0 offset:34048
	v_fmac_f32_dpp v104, -v129, v108 row_newbcast:0 row_mask:0xf bank_mask:0xf
	v_mul_f32_dpp v141, v129, v108 row_newbcast:4 row_mask:0xf bank_mask:0xf
	v_mul_f32_e32 v138, s77, v104
	v_mul_f32_dpp v139, v129, v108 row_newbcast:8 row_mask:0xf bank_mask:0xf
	v_fmac_f32_e32 v141, s79, v138
	v_mul_f32_dpp v143, v129, v108 row_newbcast:12 row_mask:0xf bank_mask:0xf
	v_fma_f32 v105, -s80, v141, v105
	v_mul_f32_e32 v144, s80, v138
	v_mul_f32_e32 v140, s81, v105
	v_fmac_f32_e32 v139, s78, v138
	v_pk_fma_f32 v[2:3], v[56:57], v[144:145], v[2:3] op_sel_hi:[1,0,1]
	v_fmac_f32_e32 v143, s83, v138
	v_pk_fma_f32 v[4:5], v[58:59], v[144:145], v[4:5] op_sel_hi:[1,0,1]
	v_pk_fma_f32 v[6:7], v[60:61], v[144:145], v[6:7] op_sel_hi:[1,0,1]
	v_pk_fma_f32 v[8:9], v[62:63], v[144:145], v[8:9] op_sel_hi:[1,0,1]
	v_pk_fma_f32 v[2:3], v[64:65], v[140:141], v[2:3] op_sel_hi:[1,0,1]
	v_pk_fma_f32 v[4:5], v[66:67], v[140:141], v[4:5] op_sel_hi:[1,0,1]
	v_pk_fma_f32 v[6:7], v[68:69], v[140:141], v[6:7] op_sel_hi:[1,0,1]
	v_pk_fma_f32 v[8:9], v[70:71], v[140:141], v[8:9] op_sel_hi:[1,0,1]
	s_waitcnt lgkmcnt(0)
	s_load_dwordx8 s[4:11], s[96:97], 0x160
	v_mov_b32_e32 v108, s88
	v_pk_mul_f32 v[124:125], v[2:3], v[72:73]
	v_mul_f32_e32 v143, s80, v143
	v_pk_mul_f32 v[126:127], v[2:3], v[88:89]
	v_fmac_f32_e32 v143, s82, v140
	v_pk_mul_f32 v[128:129], v[2:3], v[80:81]
	ds_write2_b32 v55, v139, v143 offset0:0 offset1:16
	v_pk_mul_f32 v[134:135], v[2:3], v[96:97]
	ds_read_b128 v[56:59], v0 offset:34816
	v_pk_fma_f32 v[124:125], v[4:5], v[74:75], v[124:125]
	ds_read_b128 v[60:63], v0 offset:35072
	v_pk_fma_f32 v[126:127], v[4:5], v[90:91], v[126:127]
	ds_read_b128 v[64:67], v0 offset:36352
	v_pk_fma_f32 v[128:129], v[4:5], v[82:83], v[128:129]
	ds_read_b128 v[68:71], v0 offset:36608
	v_pk_fma_f32 v[134:135], v[4:5], v[98:99], v[134:135]
	ds_read2st64_b32 v[104:105], v43 offset0:140 offset1:146
	v_pk_fma_f32 v[124:125], v[6:7], v[76:77], v[124:125]
	v_pk_fma_f32 v[126:127], v[6:7], v[92:93], v[126:127]
	v_pk_fma_f32 v[128:129], v[6:7], v[84:85], v[128:129]
	v_pk_fma_f32 v[134:135], v[6:7], v[100:101], v[134:135]
	v_pk_fma_f32 v[124:125], v[8:9], v[78:79], v[124:125]
	v_pk_fma_f32 v[126:127], v[8:9], v[94:95], v[126:127]
	v_pk_fma_f32 v[128:129], v[8:9], v[86:87], v[128:129]
	v_pk_fma_f32 v[134:135], v[8:9], v[102:103], v[134:135]
	v_add_f32_e32 v124, v124, v125
	v_add_f32_e32 v126, v126, v127
	v_add_f32_e32 v128, v128, v129
	v_add_f32_e32 v134, v134, v135
	v_mul_f32_e32 v142, s92, v108
	v_add_f32_dpp v125, v124, v124 row_mirror row_mask:0xf bank_mask:0xf
	v_add_f32_dpp v125, v126, v126 row_mirror row_mask:0xf bank_mask:0xc
	v_add_f32_dpp v127, v128, v128 row_mirror row_mask:0xf bank_mask:0xf
	v_add_f32_dpp v127, v134, v134 row_mirror row_mask:0xf bank_mask:0xc
	v_add_f32_dpp v129, v125, v125 row_half_mirror row_mask:0xf bank_mask:0xf
	v_pk_mul_f32 v[2:3], v[2:3], v[142:143] op_sel_hi:[1,0]
	v_pk_mul_f32 v[4:5], v[4:5], v[142:143] op_sel_hi:[1,0]
	v_add_f32_dpp v129, v127, v127 row_half_mirror row_mask:0xf bank_mask:0xa
	v_pk_mul_f32 v[6:7], v[6:7], v[142:143] op_sel_hi:[1,0]
	v_pk_mul_f32 v[8:9], v[8:9], v[142:143] op_sel_hi:[1,0]
	v_add_f32_dpp v129, v129, v129 quad_perm:[1,0,3,2] row_mask:0xf bank_mask:0xf
	ds_read_b128 v[88:91], v0 offset:35328
	ds_read_b128 v[92:95], v0 offset:35584
	v_add_f32_dpp v129, v129, v129 quad_perm:[2,3,0,1] row_mask:0xf bank_mask:0xf
	ds_read_b128 v[96:99], v0 offset:36864
	ds_read_b128 v[100:103], v0 offset:37120
	v_fmac_f32_dpp v106, -v129, v108 row_newbcast:0 row_mask:0xf bank_mask:0xf
	v_mul_f32_dpp v141, v129, v108 row_newbcast:4 row_mask:0xf bank_mask:0xf
	v_mul_f32_e32 v138, s89, v106
	v_mul_f32_dpp v139, v129, v108 row_newbcast:8 row_mask:0xf bank_mask:0xf
	v_fmac_f32_e32 v141, s91, v138
	v_mul_f32_dpp v143, v129, v108 row_newbcast:12 row_mask:0xf bank_mask:0xf
	v_fma_f32 v107, -s92, v141, v107
	v_mul_f32_e32 v144, s92, v138
	v_mul_f32_e32 v140, s93, v107
	v_fmac_f32_e32 v139, s90, v138
	v_pk_fma_f32 v[2:3], v[72:73], v[144:145], v[2:3] op_sel_hi:[1,0,1]
	v_fmac_f32_e32 v143, s95, v138
	v_pk_fma_f32 v[4:5], v[74:75], v[144:145], v[4:5] op_sel_hi:[1,0,1]
	v_pk_fma_f32 v[6:7], v[76:77], v[144:145], v[6:7] op_sel_hi:[1,0,1]
	v_pk_fma_f32 v[8:9], v[78:79], v[144:145], v[8:9] op_sel_hi:[1,0,1]
	v_pk_fma_f32 v[2:3], v[80:81], v[140:141], v[2:3] op_sel_hi:[1,0,1]
	v_pk_fma_f32 v[4:5], v[82:83], v[140:141], v[4:5] op_sel_hi:[1,0,1]
	v_pk_fma_f32 v[6:7], v[84:85], v[140:141], v[6:7] op_sel_hi:[1,0,1]
	v_pk_fma_f32 v[8:9], v[86:87], v[140:141], v[8:9] op_sel_hi:[1,0,1]
	s_waitcnt lgkmcnt(0)
	s_load_dwordx8 s[76:83], s[96:97], 0x180
	v_mov_b32_e32 v108, s28
	v_pk_mul_f32 v[124:125], v[2:3], v[56:57]
	v_mul_f32_e32 v143, s92, v143
	v_pk_mul_f32 v[126:127], v[2:3], v[88:89]
	v_fmac_f32_e32 v143, s94, v140
	v_pk_mul_f32 v[128:129], v[2:3], v[64:65]
	ds_write2_b32 v55, v139, v143 offset0:32 offset1:48
	v_pk_mul_f32 v[134:135], v[2:3], v[96:97]
	ds_read_b128 v[72:75], v0 offset:37888
	v_pk_fma_f32 v[124:125], v[4:5], v[58:59], v[124:125]
	ds_read_b128 v[76:79], v0 offset:38144
	v_pk_fma_f32 v[126:127], v[4:5], v[90:91], v[126:127]
	ds_read_b128 v[80:83], v0 offset:39424
	v_pk_fma_f32 v[128:129], v[4:5], v[66:67], v[128:129]
	ds_read_b128 v[84:87], v0 offset:39680
	v_pk_fma_f32 v[134:135], v[4:5], v[98:99], v[134:135]
	ds_read2st64_b32 v[106:107], v43 offset0:152 offset1:158
	v_pk_fma_f32 v[124:125], v[6:7], v[60:61], v[124:125]
	v_pk_fma_f32 v[126:127], v[6:7], v[92:93], v[126:127]
	v_pk_fma_f32 v[128:129], v[6:7], v[68:69], v[128:129]
	v_pk_fma_f32 v[134:135], v[6:7], v[100:101], v[134:135]
	v_pk_fma_f32 v[124:125], v[8:9], v[62:63], v[124:125]
	v_pk_fma_f32 v[126:127], v[8:9], v[94:95], v[126:127]
	v_pk_fma_f32 v[128:129], v[8:9], v[70:71], v[128:129]
	v_pk_fma_f32 v[134:135], v[8:9], v[102:103], v[134:135]
	v_add_f32_e32 v124, v124, v125
	v_add_f32_e32 v126, v126, v127
	v_add_f32_e32 v128, v128, v129
	v_add_f32_e32 v134, v134, v135
	v_mul_f32_e32 v142, s32, v108
	v_add_f32_dpp v125, v124, v124 row_mirror row_mask:0xf bank_mask:0xf
	v_add_f32_dpp v125, v126, v126 row_mirror row_mask:0xf bank_mask:0xc
	v_add_f32_dpp v127, v128, v128 row_mirror row_mask:0xf bank_mask:0xf
	v_add_f32_dpp v127, v134, v134 row_mirror row_mask:0xf bank_mask:0xc
	v_add_f32_dpp v129, v125, v125 row_half_mirror row_mask:0xf bank_mask:0xf
	v_pk_mul_f32 v[2:3], v[2:3], v[142:143] op_sel_hi:[1,0]
	v_pk_mul_f32 v[4:5], v[4:5], v[142:143] op_sel_hi:[1,0]
	v_add_f32_dpp v129, v127, v127 row_half_mirror row_mask:0xf bank_mask:0xa
	v_pk_mul_f32 v[6:7], v[6:7], v[142:143] op_sel_hi:[1,0]
	v_pk_mul_f32 v[8:9], v[8:9], v[142:143] op_sel_hi:[1,0]
	v_add_f32_dpp v129, v129, v129 quad_perm:[1,0,3,2] row_mask:0xf bank_mask:0xf
	ds_read_b128 v[88:91], v0 offset:38400
	ds_read_b128 v[92:95], v0 offset:38656
	v_add_f32_dpp v129, v129, v129 quad_perm:[2,3,0,1] row_mask:0xf bank_mask:0xf
	ds_read_b128 v[96:99], v0 offset:39936
	ds_read_b128 v[100:103], v0 offset:40192
	v_fmac_f32_dpp v104, -v129, v108 row_newbcast:0 row_mask:0xf bank_mask:0xf
	v_mul_f32_dpp v141, v129, v108 row_newbcast:4 row_mask:0xf bank_mask:0xf
	v_mul_f32_e32 v138, s29, v104
	v_mul_f32_dpp v139, v129, v108 row_newbcast:8 row_mask:0xf bank_mask:0xf
	v_fmac_f32_e32 v141, s31, v138
	v_mul_f32_dpp v143, v129, v108 row_newbcast:12 row_mask:0xf bank_mask:0xf
	v_fma_f32 v105, -s32, v141, v105
	v_mul_f32_e32 v144, s32, v138
	v_mul_f32_e32 v140, s33, v105
	v_fmac_f32_e32 v139, s30, v138
	v_pk_fma_f32 v[2:3], v[56:57], v[144:145], v[2:3] op_sel_hi:[1,0,1]
	v_fmac_f32_e32 v143, s35, v138
	v_pk_fma_f32 v[4:5], v[58:59], v[144:145], v[4:5] op_sel_hi:[1,0,1]
	v_pk_fma_f32 v[6:7], v[60:61], v[144:145], v[6:7] op_sel_hi:[1,0,1]
	v_pk_fma_f32 v[8:9], v[62:63], v[144:145], v[8:9] op_sel_hi:[1,0,1]
	v_pk_fma_f32 v[2:3], v[64:65], v[140:141], v[2:3] op_sel_hi:[1,0,1]
	v_pk_fma_f32 v[4:5], v[66:67], v[140:141], v[4:5] op_sel_hi:[1,0,1]
	v_pk_fma_f32 v[6:7], v[68:69], v[140:141], v[6:7] op_sel_hi:[1,0,1]
	v_pk_fma_f32 v[8:9], v[70:71], v[140:141], v[8:9] op_sel_hi:[1,0,1]
	s_waitcnt lgkmcnt(0)
	s_load_dwordx8 s[88:95], s[96:97], 0x1a0
	v_mov_b32_e32 v108, s4
	v_pk_mul_f32 v[124:125], v[2:3], v[72:73]
	v_mul_f32_e32 v143, s32, v143
	v_pk_mul_f32 v[126:127], v[2:3], v[88:89]
	v_fmac_f32_e32 v143, s34, v140
	v_pk_mul_f32 v[128:129], v[2:3], v[80:81]
	ds_write2_b32 v55, v139, v143 offset0:64 offset1:80
	v_pk_mul_f32 v[134:135], v[2:3], v[96:97]
	ds_read_b128 v[56:59], v0 offset:40960
	v_pk_fma_f32 v[124:125], v[4:5], v[74:75], v[124:125]
	ds_read_b128 v[60:63], v0 offset:41216
	v_pk_fma_f32 v[126:127], v[4:5], v[90:91], v[126:127]
	ds_read_b128 v[64:67], v0 offset:42496
	v_pk_fma_f32 v[128:129], v[4:5], v[82:83], v[128:129]
	ds_read_b128 v[68:71], v0 offset:42752
	v_pk_fma_f32 v[134:135], v[4:5], v[98:99], v[134:135]
	ds_read2st64_b32 v[104:105], v43 offset0:164 offset1:170
	v_pk_fma_f32 v[124:125], v[6:7], v[76:77], v[124:125]
	v_pk_fma_f32 v[126:127], v[6:7], v[92:93], v[126:127]
	v_pk_fma_f32 v[128:129], v[6:7], v[84:85], v[128:129]
	v_pk_fma_f32 v[134:135], v[6:7], v[100:101], v[134:135]
	v_pk_fma_f32 v[124:125], v[8:9], v[78:79], v[124:125]
	v_pk_fma_f32 v[126:127], v[8:9], v[94:95], v[126:127]
	v_pk_fma_f32 v[128:129], v[8:9], v[86:87], v[128:129]
	v_pk_fma_f32 v[134:135], v[8:9], v[102:103], v[134:135]
	v_add_f32_e32 v124, v124, v125
	v_add_f32_e32 v126, v126, v127
	v_add_f32_e32 v128, v128, v129
	v_add_f32_e32 v134, v134, v135
	v_mul_f32_e32 v142, s8, v108
	v_add_f32_dpp v125, v124, v124 row_mirror row_mask:0xf bank_mask:0xf
	v_add_f32_dpp v125, v126, v126 row_mirror row_mask:0xf bank_mask:0xc
	v_add_f32_dpp v127, v128, v128 row_mirror row_mask:0xf bank_mask:0xf
	v_add_f32_dpp v127, v134, v134 row_mirror row_mask:0xf bank_mask:0xc
	v_add_f32_dpp v129, v125, v125 row_half_mirror row_mask:0xf bank_mask:0xf
	v_pk_mul_f32 v[2:3], v[2:3], v[142:143] op_sel_hi:[1,0]
	v_pk_mul_f32 v[4:5], v[4:5], v[142:143] op_sel_hi:[1,0]
	v_add_f32_dpp v129, v127, v127 row_half_mirror row_mask:0xf bank_mask:0xa
	v_pk_mul_f32 v[6:7], v[6:7], v[142:143] op_sel_hi:[1,0]
	v_pk_mul_f32 v[8:9], v[8:9], v[142:143] op_sel_hi:[1,0]
	v_add_f32_dpp v129, v129, v129 quad_perm:[1,0,3,2] row_mask:0xf bank_mask:0xf
	ds_read_b128 v[88:91], v0 offset:41472
	ds_read_b128 v[92:95], v0 offset:41728
	v_add_f32_dpp v129, v129, v129 quad_perm:[2,3,0,1] row_mask:0xf bank_mask:0xf
	ds_read_b128 v[96:99], v0 offset:43008
	ds_read_b128 v[100:103], v0 offset:43264
	v_fmac_f32_dpp v106, -v129, v108 row_newbcast:0 row_mask:0xf bank_mask:0xf
	v_mul_f32_dpp v141, v129, v108 row_newbcast:4 row_mask:0xf bank_mask:0xf
	v_mul_f32_e32 v138, s5, v106
	v_mul_f32_dpp v139, v129, v108 row_newbcast:8 row_mask:0xf bank_mask:0xf
	v_fmac_f32_e32 v141, s7, v138
	v_mul_f32_dpp v143, v129, v108 row_newbcast:12 row_mask:0xf bank_mask:0xf
	v_fma_f32 v107, -s8, v141, v107
	v_mul_f32_e32 v144, s8, v138
	v_mul_f32_e32 v140, s9, v107
	v_fmac_f32_e32 v139, s6, v138
	v_pk_fma_f32 v[2:3], v[72:73], v[144:145], v[2:3] op_sel_hi:[1,0,1]
	v_fmac_f32_e32 v143, s11, v138
	v_pk_fma_f32 v[4:5], v[74:75], v[144:145], v[4:5] op_sel_hi:[1,0,1]
	v_pk_fma_f32 v[6:7], v[76:77], v[144:145], v[6:7] op_sel_hi:[1,0,1]
	v_pk_fma_f32 v[8:9], v[78:79], v[144:145], v[8:9] op_sel_hi:[1,0,1]
	v_pk_fma_f32 v[2:3], v[80:81], v[140:141], v[2:3] op_sel_hi:[1,0,1]
	v_pk_fma_f32 v[4:5], v[82:83], v[140:141], v[4:5] op_sel_hi:[1,0,1]
	v_pk_fma_f32 v[6:7], v[84:85], v[140:141], v[6:7] op_sel_hi:[1,0,1]
	v_pk_fma_f32 v[8:9], v[86:87], v[140:141], v[8:9] op_sel_hi:[1,0,1]
	s_waitcnt lgkmcnt(0)
	s_load_dwordx8 s[28:35], s[96:97], 0x1c0
	v_mov_b32_e32 v108, s76
	v_pk_mul_f32 v[124:125], v[2:3], v[56:57]
	v_mul_f32_e32 v143, s8, v143
	v_pk_mul_f32 v[126:127], v[2:3], v[88:89]
	v_fmac_f32_e32 v143, s10, v140
	v_pk_mul_f32 v[128:129], v[2:3], v[64:65]
	ds_write2_b32 v55, v139, v143 offset0:96 offset1:112
	v_pk_mul_f32 v[134:135], v[2:3], v[96:97]
	ds_read_b128 v[72:75], v0 offset:44032
	v_pk_fma_f32 v[124:125], v[4:5], v[58:59], v[124:125]
	ds_read_b128 v[76:79], v0 offset:44288
	v_pk_fma_f32 v[126:127], v[4:5], v[90:91], v[126:127]
	ds_read_b128 v[80:83], v0 offset:45568
	v_pk_fma_f32 v[128:129], v[4:5], v[66:67], v[128:129]
	ds_read_b128 v[84:87], v0 offset:45824
	v_pk_fma_f32 v[134:135], v[4:5], v[98:99], v[134:135]
	ds_read2st64_b32 v[106:107], v43 offset0:176 offset1:182
	v_pk_fma_f32 v[124:125], v[6:7], v[60:61], v[124:125]
	v_pk_fma_f32 v[126:127], v[6:7], v[92:93], v[126:127]
	v_pk_fma_f32 v[128:129], v[6:7], v[68:69], v[128:129]
	v_pk_fma_f32 v[134:135], v[6:7], v[100:101], v[134:135]
	v_pk_fma_f32 v[124:125], v[8:9], v[62:63], v[124:125]
	v_pk_fma_f32 v[126:127], v[8:9], v[94:95], v[126:127]
	v_pk_fma_f32 v[128:129], v[8:9], v[70:71], v[128:129]
	v_pk_fma_f32 v[134:135], v[8:9], v[102:103], v[134:135]
	v_add_f32_e32 v124, v124, v125
	v_add_f32_e32 v126, v126, v127
	v_add_f32_e32 v128, v128, v129
	v_add_f32_e32 v134, v134, v135
	v_mul_f32_e32 v142, s80, v108
	v_add_f32_dpp v125, v124, v124 row_mirror row_mask:0xf bank_mask:0xf
	v_add_f32_dpp v125, v126, v126 row_mirror row_mask:0xf bank_mask:0xc
	v_add_f32_dpp v127, v128, v128 row_mirror row_mask:0xf bank_mask:0xf
	v_add_f32_dpp v127, v134, v134 row_mirror row_mask:0xf bank_mask:0xc
	v_add_f32_dpp v129, v125, v125 row_half_mirror row_mask:0xf bank_mask:0xf
	v_pk_mul_f32 v[2:3], v[2:3], v[142:143] op_sel_hi:[1,0]
	v_pk_mul_f32 v[4:5], v[4:5], v[142:143] op_sel_hi:[1,0]
	v_add_f32_dpp v129, v127, v127 row_half_mirror row_mask:0xf bank_mask:0xa
	v_pk_mul_f32 v[6:7], v[6:7], v[142:143] op_sel_hi:[1,0]
	v_pk_mul_f32 v[8:9], v[8:9], v[142:143] op_sel_hi:[1,0]
	v_add_f32_dpp v129, v129, v129 quad_perm:[1,0,3,2] row_mask:0xf bank_mask:0xf
	ds_read_b128 v[88:91], v0 offset:44544
	ds_read_b128 v[92:95], v0 offset:44800
	v_add_f32_dpp v129, v129, v129 quad_perm:[2,3,0,1] row_mask:0xf bank_mask:0xf
	ds_read_b128 v[96:99], v0 offset:46080
	ds_read_b128 v[100:103], v0 offset:46336
	v_fmac_f32_dpp v104, -v129, v108 row_newbcast:0 row_mask:0xf bank_mask:0xf
	v_mul_f32_dpp v141, v129, v108 row_newbcast:4 row_mask:0xf bank_mask:0xf
	v_mul_f32_e32 v138, s77, v104
	v_mul_f32_dpp v139, v129, v108 row_newbcast:8 row_mask:0xf bank_mask:0xf
	v_fmac_f32_e32 v141, s79, v138
	v_mul_f32_dpp v143, v129, v108 row_newbcast:12 row_mask:0xf bank_mask:0xf
	v_fma_f32 v105, -s80, v141, v105
	v_mul_f32_e32 v144, s80, v138
	v_mul_f32_e32 v140, s81, v105
	v_fmac_f32_e32 v139, s78, v138
	v_pk_fma_f32 v[2:3], v[56:57], v[144:145], v[2:3] op_sel_hi:[1,0,1]
	v_fmac_f32_e32 v143, s83, v138
	v_pk_fma_f32 v[4:5], v[58:59], v[144:145], v[4:5] op_sel_hi:[1,0,1]
	v_pk_fma_f32 v[6:7], v[60:61], v[144:145], v[6:7] op_sel_hi:[1,0,1]
	v_pk_fma_f32 v[8:9], v[62:63], v[144:145], v[8:9] op_sel_hi:[1,0,1]
	v_pk_fma_f32 v[2:3], v[64:65], v[140:141], v[2:3] op_sel_hi:[1,0,1]
	v_pk_fma_f32 v[4:5], v[66:67], v[140:141], v[4:5] op_sel_hi:[1,0,1]
	v_pk_fma_f32 v[6:7], v[68:69], v[140:141], v[6:7] op_sel_hi:[1,0,1]
	v_pk_fma_f32 v[8:9], v[70:71], v[140:141], v[8:9] op_sel_hi:[1,0,1]
	s_waitcnt lgkmcnt(0)
	s_load_dwordx8 s[4:11], s[96:97], 0x1e0
	v_mov_b32_e32 v108, s88
	v_pk_mul_f32 v[124:125], v[2:3], v[72:73]
	v_mul_f32_e32 v143, s80, v143
	v_pk_mul_f32 v[126:127], v[2:3], v[88:89]
	v_fmac_f32_e32 v143, s82, v140
	v_pk_mul_f32 v[128:129], v[2:3], v[80:81]
	ds_write2_b32 v55, v139, v143 offset0:128 offset1:144
	v_pk_mul_f32 v[134:135], v[2:3], v[96:97]
	ds_read_b128 v[56:59], v0 offset:47104
	v_pk_fma_f32 v[124:125], v[4:5], v[74:75], v[124:125]
	ds_read_b128 v[60:63], v0 offset:47360
	v_pk_fma_f32 v[126:127], v[4:5], v[90:91], v[126:127]
	ds_read_b128 v[64:67], v0 offset:48640
	v_pk_fma_f32 v[128:129], v[4:5], v[82:83], v[128:129]
	ds_read_b128 v[68:71], v0 offset:48896
	v_pk_fma_f32 v[134:135], v[4:5], v[98:99], v[134:135]
	ds_read2st64_b32 v[104:105], v43 offset0:188 offset1:194
	v_pk_fma_f32 v[124:125], v[6:7], v[76:77], v[124:125]
	v_pk_fma_f32 v[126:127], v[6:7], v[92:93], v[126:127]
	v_pk_fma_f32 v[128:129], v[6:7], v[84:85], v[128:129]
	v_pk_fma_f32 v[134:135], v[6:7], v[100:101], v[134:135]
	v_pk_fma_f32 v[124:125], v[8:9], v[78:79], v[124:125]
	v_pk_fma_f32 v[126:127], v[8:9], v[94:95], v[126:127]
	v_pk_fma_f32 v[128:129], v[8:9], v[86:87], v[128:129]
	v_pk_fma_f32 v[134:135], v[8:9], v[102:103], v[134:135]
	v_add_f32_e32 v124, v124, v125
	v_add_f32_e32 v126, v126, v127
	v_add_f32_e32 v128, v128, v129
	v_add_f32_e32 v134, v134, v135
	v_mul_f32_e32 v142, s92, v108
	v_add_f32_dpp v125, v124, v124 row_mirror row_mask:0xf bank_mask:0xf
	v_add_f32_dpp v125, v126, v126 row_mirror row_mask:0xf bank_mask:0xc
	v_add_f32_dpp v127, v128, v128 row_mirror row_mask:0xf bank_mask:0xf
	v_add_f32_dpp v127, v134, v134 row_mirror row_mask:0xf bank_mask:0xc
	v_add_f32_dpp v129, v125, v125 row_half_mirror row_mask:0xf bank_mask:0xf
	v_pk_mul_f32 v[2:3], v[2:3], v[142:143] op_sel_hi:[1,0]
	v_pk_mul_f32 v[4:5], v[4:5], v[142:143] op_sel_hi:[1,0]
	v_add_f32_dpp v129, v127, v127 row_half_mirror row_mask:0xf bank_mask:0xa
	v_pk_mul_f32 v[6:7], v[6:7], v[142:143] op_sel_hi:[1,0]
	v_pk_mul_f32 v[8:9], v[8:9], v[142:143] op_sel_hi:[1,0]
	v_add_f32_dpp v129, v129, v129 quad_perm:[1,0,3,2] row_mask:0xf bank_mask:0xf
	ds_read_b128 v[88:91], v0 offset:47616
	ds_read_b128 v[92:95], v0 offset:47872
	v_add_f32_dpp v129, v129, v129 quad_perm:[2,3,0,1] row_mask:0xf bank_mask:0xf
	ds_read_b128 v[96:99], v0 offset:49152
	ds_read_b128 v[100:103], v0 offset:49408
	v_fmac_f32_dpp v106, -v129, v108 row_newbcast:0 row_mask:0xf bank_mask:0xf
	v_mul_f32_dpp v141, v129, v108 row_newbcast:4 row_mask:0xf bank_mask:0xf
	v_mul_f32_e32 v138, s89, v106
	v_mul_f32_dpp v139, v129, v108 row_newbcast:8 row_mask:0xf bank_mask:0xf
	v_fmac_f32_e32 v141, s91, v138
	v_mul_f32_dpp v143, v129, v108 row_newbcast:12 row_mask:0xf bank_mask:0xf
	v_fma_f32 v107, -s92, v141, v107
	v_mul_f32_e32 v144, s92, v138
	v_mul_f32_e32 v140, s93, v107
	v_fmac_f32_e32 v139, s90, v138
	v_pk_fma_f32 v[2:3], v[72:73], v[144:145], v[2:3] op_sel_hi:[1,0,1]
	v_fmac_f32_e32 v143, s95, v138
	v_pk_fma_f32 v[4:5], v[74:75], v[144:145], v[4:5] op_sel_hi:[1,0,1]
	v_pk_fma_f32 v[6:7], v[76:77], v[144:145], v[6:7] op_sel_hi:[1,0,1]
	v_pk_fma_f32 v[8:9], v[78:79], v[144:145], v[8:9] op_sel_hi:[1,0,1]
	v_pk_fma_f32 v[2:3], v[80:81], v[140:141], v[2:3] op_sel_hi:[1,0,1]
	v_pk_fma_f32 v[4:5], v[82:83], v[140:141], v[4:5] op_sel_hi:[1,0,1]
	v_pk_fma_f32 v[6:7], v[84:85], v[140:141], v[6:7] op_sel_hi:[1,0,1]
	v_pk_fma_f32 v[8:9], v[86:87], v[140:141], v[8:9] op_sel_hi:[1,0,1]
	s_waitcnt lgkmcnt(0)
	s_add_i32 m0, s39, 1
	s_min_u32 m0, m0, 0x1ff
	s_lshl_b32 m0, m0, 9
	s_add_u32 s96, s100, m0
	s_addc_u32 s97, s101, 0
	s_load_dwordx8 s[76:83], s[96:97], 0x0
	v_mov_b32_e32 v108, s28
	v_pk_mul_f32 v[124:125], v[2:3], v[56:57]
	v_mul_f32_e32 v143, s92, v143
	v_pk_mul_f32 v[126:127], v[2:3], v[88:89]
	v_fmac_f32_e32 v143, s94, v140
	v_pk_mul_f32 v[128:129], v[2:3], v[64:65]
	ds_write2_b32 v55, v139, v143 offset0:160 offset1:176
	v_pk_mul_f32 v[134:135], v[2:3], v[96:97]
	ds_read_b128 v[72:75], v0 offset:50176
	v_pk_fma_f32 v[124:125], v[4:5], v[58:59], v[124:125]
	ds_read_b128 v[76:79], v0 offset:50432
	v_pk_fma_f32 v[126:127], v[4:5], v[90:91], v[126:127]
	ds_read_b128 v[80:83], v0 offset:51712
	v_pk_fma_f32 v[128:129], v[4:5], v[66:67], v[128:129]
	ds_read_b128 v[84:87], v0 offset:51968
	v_pk_fma_f32 v[134:135], v[4:5], v[98:99], v[134:135]
	ds_read2st64_b32 v[106:107], v43 offset0:200 offset1:206
	v_pk_fma_f32 v[124:125], v[6:7], v[60:61], v[124:125]
	v_pk_fma_f32 v[126:127], v[6:7], v[92:93], v[126:127]
	v_pk_fma_f32 v[128:129], v[6:7], v[68:69], v[128:129]
	v_pk_fma_f32 v[134:135], v[6:7], v[100:101], v[134:135]
	v_pk_fma_f32 v[124:125], v[8:9], v[62:63], v[124:125]
	v_pk_fma_f32 v[126:127], v[8:9], v[94:95], v[126:127]
	v_pk_fma_f32 v[128:129], v[8:9], v[70:71], v[128:129]
	v_pk_fma_f32 v[134:135], v[8:9], v[102:103], v[134:135]
	v_add_f32_e32 v124, v124, v125
	v_add_f32_e32 v126, v126, v127
	v_add_f32_e32 v128, v128, v129
	v_add_f32_e32 v134, v134, v135
	v_mul_f32_e32 v142, s32, v108
	v_add_f32_dpp v125, v124, v124 row_mirror row_mask:0xf bank_mask:0xf
	v_add_f32_dpp v125, v126, v126 row_mirror row_mask:0xf bank_mask:0xc
	v_add_f32_dpp v127, v128, v128 row_mirror row_mask:0xf bank_mask:0xf
	v_add_f32_dpp v127, v134, v134 row_mirror row_mask:0xf bank_mask:0xc
	v_add_f32_dpp v129, v125, v125 row_half_mirror row_mask:0xf bank_mask:0xf
	v_pk_mul_f32 v[2:3], v[2:3], v[142:143] op_sel_hi:[1,0]
	v_pk_mul_f32 v[4:5], v[4:5], v[142:143] op_sel_hi:[1,0]
	v_add_f32_dpp v129, v127, v127 row_half_mirror row_mask:0xf bank_mask:0xa
	v_pk_mul_f32 v[6:7], v[6:7], v[142:143] op_sel_hi:[1,0]
	v_pk_mul_f32 v[8:9], v[8:9], v[142:143] op_sel_hi:[1,0]
	v_add_f32_dpp v129, v129, v129 quad_perm:[1,0,3,2] row_mask:0xf bank_mask:0xf
	ds_read_b128 v[88:91], v0 offset:50688
	ds_read_b128 v[92:95], v0 offset:50944
	v_add_f32_dpp v129, v129, v129 quad_perm:[2,3,0,1] row_mask:0xf bank_mask:0xf
	ds_read_b128 v[96:99], v0 offset:52224
	ds_read_b128 v[100:103], v0 offset:52480
	v_fmac_f32_dpp v104, -v129, v108 row_newbcast:0 row_mask:0xf bank_mask:0xf
	v_mul_f32_dpp v141, v129, v108 row_newbcast:4 row_mask:0xf bank_mask:0xf
	v_mul_f32_e32 v138, s29, v104
	v_mul_f32_dpp v139, v129, v108 row_newbcast:8 row_mask:0xf bank_mask:0xf
	v_fmac_f32_e32 v141, s31, v138
	v_mul_f32_dpp v143, v129, v108 row_newbcast:12 row_mask:0xf bank_mask:0xf
	v_fma_f32 v105, -s32, v141, v105
	v_mul_f32_e32 v144, s32, v138
	v_mul_f32_e32 v140, s33, v105
	v_fmac_f32_e32 v139, s30, v138
	v_pk_fma_f32 v[2:3], v[56:57], v[144:145], v[2:3] op_sel_hi:[1,0,1]
	v_fmac_f32_e32 v143, s35, v138
	v_pk_fma_f32 v[4:5], v[58:59], v[144:145], v[4:5] op_sel_hi:[1,0,1]
	v_pk_fma_f32 v[6:7], v[60:61], v[144:145], v[6:7] op_sel_hi:[1,0,1]
	v_pk_fma_f32 v[8:9], v[62:63], v[144:145], v[8:9] op_sel_hi:[1,0,1]
	v_pk_fma_f32 v[2:3], v[64:65], v[140:141], v[2:3] op_sel_hi:[1,0,1]
	v_pk_fma_f32 v[4:5], v[66:67], v[140:141], v[4:5] op_sel_hi:[1,0,1]
	v_pk_fma_f32 v[6:7], v[68:69], v[140:141], v[6:7] op_sel_hi:[1,0,1]
	v_pk_fma_f32 v[8:9], v[70:71], v[140:141], v[8:9] op_sel_hi:[1,0,1]
	s_waitcnt lgkmcnt(0)
	s_load_dwordx8 s[88:95], s[96:97], 0x20
	v_mov_b32_e32 v108, s4
	v_pk_mul_f32 v[124:125], v[2:3], v[72:73]
	v_mul_f32_e32 v143, s32, v143
	v_pk_mul_f32 v[126:127], v[2:3], v[88:89]
	v_fmac_f32_e32 v143, s34, v140
	v_pk_mul_f32 v[128:129], v[2:3], v[80:81]
	ds_write2_b32 v55, v139, v143 offset0:192 offset1:208
	v_pk_mul_f32 v[134:135], v[2:3], v[96:97]
	v_pk_fma_f32 v[124:125], v[4:5], v[74:75], v[124:125]
	v_pk_fma_f32 v[126:127], v[4:5], v[90:91], v[126:127]
	v_pk_fma_f32 v[128:129], v[4:5], v[82:83], v[128:129]
	v_pk_fma_f32 v[134:135], v[4:5], v[98:99], v[134:135]
	v_pk_fma_f32 v[124:125], v[6:7], v[76:77], v[124:125]
	v_pk_fma_f32 v[126:127], v[6:7], v[92:93], v[126:127]
	v_pk_fma_f32 v[128:129], v[6:7], v[84:85], v[128:129]
	v_pk_fma_f32 v[134:135], v[6:7], v[100:101], v[134:135]
	v_pk_fma_f32 v[124:125], v[8:9], v[78:79], v[124:125]
	v_pk_fma_f32 v[126:127], v[8:9], v[94:95], v[126:127]
	v_pk_fma_f32 v[128:129], v[8:9], v[86:87], v[128:129]
	v_pk_fma_f32 v[134:135], v[8:9], v[102:103], v[134:135]
	v_add_f32_e32 v124, v124, v125
	v_add_f32_e32 v126, v126, v127
	v_add_f32_e32 v128, v128, v129
	v_add_f32_e32 v134, v134, v135
	v_mul_f32_e32 v142, s8, v108
	v_add_f32_dpp v125, v124, v124 row_mirror row_mask:0xf bank_mask:0xf
	v_add_f32_dpp v125, v126, v126 row_mirror row_mask:0xf bank_mask:0xc
	v_add_f32_dpp v127, v128, v128 row_mirror row_mask:0xf bank_mask:0xf
	v_add_f32_dpp v127, v134, v134 row_mirror row_mask:0xf bank_mask:0xc
	v_add_f32_dpp v129, v125, v125 row_half_mirror row_mask:0xf bank_mask:0xf
	v_pk_mul_f32 v[2:3], v[2:3], v[142:143] op_sel_hi:[1,0]
	v_pk_mul_f32 v[4:5], v[4:5], v[142:143] op_sel_hi:[1,0]
	v_add_f32_dpp v129, v127, v127 row_half_mirror row_mask:0xf bank_mask:0xa
	v_pk_mul_f32 v[6:7], v[6:7], v[142:143] op_sel_hi:[1,0]
	v_pk_mul_f32 v[8:9], v[8:9], v[142:143] op_sel_hi:[1,0]
	v_add_f32_dpp v129, v129, v129 quad_perm:[1,0,3,2] row_mask:0xf bank_mask:0xf
	s_nop 1
	v_add_f32_dpp v129, v129, v129 quad_perm:[2,3,0,1] row_mask:0xf bank_mask:0xf
	s_nop 1
	v_fmac_f32_dpp v106, -v129, v108 row_newbcast:0 row_mask:0xf bank_mask:0xf
	v_mul_f32_dpp v141, v129, v108 row_newbcast:4 row_mask:0xf bank_mask:0xf
	v_mul_f32_e32 v138, s5, v106
	v_mul_f32_dpp v139, v129, v108 row_newbcast:8 row_mask:0xf bank_mask:0xf
	v_fmac_f32_e32 v141, s7, v138
	v_mul_f32_dpp v143, v129, v108 row_newbcast:12 row_mask:0xf bank_mask:0xf
	v_fma_f32 v107, -s8, v141, v107
	v_mul_f32_e32 v144, s8, v138
	v_mul_f32_e32 v140, s9, v107
	v_fmac_f32_e32 v139, s6, v138
	v_pk_fma_f32 v[2:3], v[72:73], v[144:145], v[2:3] op_sel_hi:[1,0,1]
	v_fmac_f32_e32 v143, s11, v138
	v_pk_fma_f32 v[4:5], v[74:75], v[144:145], v[4:5] op_sel_hi:[1,0,1]
	v_pk_fma_f32 v[6:7], v[76:77], v[144:145], v[6:7] op_sel_hi:[1,0,1]
	v_pk_fma_f32 v[8:9], v[78:79], v[144:145], v[8:9] op_sel_hi:[1,0,1]
	v_pk_fma_f32 v[2:3], v[80:81], v[140:141], v[2:3] op_sel_hi:[1,0,1]
	v_pk_fma_f32 v[4:5], v[82:83], v[140:141], v[4:5] op_sel_hi:[1,0,1]
	v_pk_fma_f32 v[6:7], v[84:85], v[140:141], v[6:7] op_sel_hi:[1,0,1]
	v_pk_fma_f32 v[8:9], v[86:87], v[140:141], v[8:9] op_sel_hi:[1,0,1]
	v_mul_f32_e32 v143, s8, v143
	v_fmac_f32_e32 v143, s10, v140
	ds_write2_b32 v55, v139, v143 offset0:224 offset1:240

.LBB0_853:
	s_add_i32 s41, s14, 1
	s_and_saveexec_b64 s[26:27], s[44:45]
	s_xor_b64 vcc, exec, s[26:27]
	s_cbranch_execz .LBB0_855
	s_and_b32 s26, s41, 1
	s_mul_i32 s27, s26, 0xc200
	s_add_i32 s27, s27, 0
	v_add_u32_e32 v0, s27, v155
	v_add_u32_e32 v158, s27, v156
	v_mov_b32_e32 v123, s27
	v_lshl_add_u32 v159, s26, 11, v154
	v_add_u32_e32 v166, 0x400, v159
	s_lshl_b32 s96, s41, 9
	s_add_u32 s96, s100, s96
	s_addc_u32 s97, s101, 0
	ds_read_b128 v[6:9], v0 offset:4096
	ds_read_b128 v[10:13], v0 offset:4352
	ds_read_b128 v[14:17], v0 offset:4608
	ds_read_b128 v[18:21], v0 offset:4864
	ds_read2st64_b32 v[62:63], v158 offset0:25 offset1:26
	ds_read_b128 v[22:25], v0 offset:5120
	ds_read_b128 v[26:29], v0 offset:5376
	ds_read_b128 v[30:33], v0 offset:5632
	ds_read_b128 v[34:37], v0 offset:5888
	ds_read_b128 v[38:41], v0 offset:6144
	s_waitcnt lgkmcnt(0)
	s_load_dwordx8 s[28:35], s[96:97], 0x40
	v_pk_mul_f32 v[82:83], v[138:139], v[6:7]
	ds_read_b128 v[42:45], v0 offset:8192
	v_pk_mul_f32 v[84:85], v[138:139], v[10:11]
	ds_read_b128 v[46:49], v0 offset:8448
	v_pk_mul_f32 v[86:87], v[138:139], v[14:15]
	ds_read_b128 v[50:53], v0 offset:8704
	v_pk_mul_f32 v[88:89], v[138:139], v[18:19]
	ds_read_b128 v[54:57], v0 offset:8960
	v_pk_fma_f32 v[82:83], v[140:141], v[8:9], v[82:83]
	ds_read_b128 v[58:61], v0 offset:9216
	v_pk_fma_f32 v[84:85], v[140:141], v[12:13], v[84:85]
	ds_read2st64_b32 v[72:73], v158 offset0:37 offset1:38
	v_pk_fma_f32 v[86:87], v[140:141], v[16:17], v[86:87]
	v_pk_fma_f32 v[88:89], v[140:141], v[20:21], v[88:89]
	v_pk_mul_f32 v[138:139], v[138:139], v[22:23]
	v_pk_mul_f32 v[140:141], v[140:141], v[24:25]
	v_add_f32_e32 v82, v82, v83
	v_add_f32_e32 v84, v84, v85
	v_add_f32_e32 v86, v86, v87
	v_add_f32_e32 v88, v88, v89
	ds_read_b128 v[6:9], v0 offset:7168
	ds_read_b128 v[10:13], v0 offset:7424
	ds_read_b128 v[14:17], v0 offset:7680
	ds_read_b128 v[18:21], v0 offset:7936
	v_add_f32_dpp v83, v82, v82 row_mirror row_mask:0xf bank_mask:0xf
	v_add_f32_dpp v83, v84, v84 row_mirror row_mask:0xf bank_mask:0xc
	v_add_f32_dpp v85, v86, v86 row_mirror row_mask:0xf bank_mask:0xf
	v_add_f32_dpp v85, v88, v88 row_mirror row_mask:0xf bank_mask:0xc
	v_add_f32_dpp v87, v83, v83 row_half_mirror row_mask:0xf bank_mask:0xf
	v_pk_fma_f32 v[138:139], v[30:31], v[62:63], v[138:139] op_sel_hi:[1,0,1]
	v_pk_fma_f32 v[140:141], v[32:33], v[62:63], v[140:141] op_sel_hi:[1,0,1]
	v_add_f32_dpp v87, v85, v85 row_half_mirror row_mask:0xf bank_mask:0xa
	v_pk_fma_f32 v[138:139], v[38:39], v[62:63], v[138:139] op_sel:[0,1,0] op_sel_hi:[1,1,1]
	v_pk_fma_f32 v[140:141], v[40:41], v[62:63], v[140:141] op_sel:[0,1,0] op_sel_hi:[1,1,1]
	v_add_f32_dpp v87, v87, v87 quad_perm:[1,0,3,2] row_mask:0xf bank_mask:0xf
	v_mul_f32_e32 v134, s77, v62
	v_mul_f32_e32 v135, s83, v62
	v_add_f32_dpp v87, v87, v87 quad_perm:[2,3,0,1] row_mask:0xf bank_mask:0xf
	v_fmac_f32_e32 v135, s81, v63
	v_mul_f32_e32 v92, s79, v62
	v_mov_b32_dpp v90, v87 row_newbcast:0 row_mask:0xf bank_mask:0xf
	v_add_f32_dpp v92, v87, v92 row_newbcast:4 row_mask:0xf bank_mask:0xf
	v_add_f32_dpp v91, v87, v134 row_newbcast:8 row_mask:0xf bank_mask:0xf
	v_pk_fma_f32 v[138:139], v[26:27], v[90:91], v[138:139] op_sel_hi:[1,0,1] neg_lo:[0,1,0] neg_hi:[0,1,0]
	v_fma_f32 v92, -v90, s78, v92
	v_pk_fma_f32 v[140:141], v[28:29], v[90:91], v[140:141] op_sel_hi:[1,0,1] neg_lo:[0,1,0] neg_hi:[0,1,0]
	v_add_f32_dpp v93, v87, v135 row_newbcast:12 row_mask:0xf bank_mask:0xf
	v_pk_fma_f32 v[138:139], v[34:35], v[92:93], v[138:139] op_sel_hi:[1,0,1] neg_lo:[0,1,0] neg_hi:[0,1,0]
	v_pk_fma_f32 v[140:141], v[36:37], v[92:93], v[140:141] op_sel_hi:[1,0,1] neg_lo:[0,1,0] neg_hi:[0,1,0]
	s_waitcnt lgkmcnt(0)
	s_load_dwordx8 s[4:11], s[96:97], 0x60
	v_pk_mul_f32 v[82:83], v[138:139], v[6:7]
	v_fma_f32 v91, -v90, s76, v91
	v_pk_mul_f32 v[84:85], v[138:139], v[10:11]
	v_fma_f32 v93, -v90, s82, v93
	v_pk_mul_f32 v[86:87], v[138:139], v[14:15]
	v_fma_f32 v93, -v92, s80, v93
	v_pk_mul_f32 v[88:89], v[138:139], v[18:19]
	ds_write2_b32 v159, v91, v93 offset0:0 offset1:16
	v_pk_fma_f32 v[82:83], v[140:141], v[8:9], v[82:83]
	ds_read_b128 v[22:25], v0 offset:11264
	v_pk_fma_f32 v[84:85], v[140:141], v[12:13], v[84:85]
	ds_read_b128 v[26:29], v0 offset:11520
	v_pk_fma_f32 v[86:87], v[140:141], v[16:17], v[86:87]
	ds_read_b128 v[30:33], v0 offset:11776
	v_pk_fma_f32 v[88:89], v[140:141], v[20:21], v[88:89]
	ds_read_b128 v[34:37], v0 offset:12032
	v_pk_mul_f32 v[138:139], v[138:139], v[42:43]
	ds_read_b128 v[38:41], v0 offset:12288
	v_pk_mul_f32 v[140:141], v[140:141], v[44:45]
	ds_read2st64_b32 v[62:63], v158 offset0:49 offset1:50
	v_add_f32_e32 v82, v82, v83
	v_add_f32_e32 v84, v84, v85
	v_add_f32_e32 v86, v86, v87
	v_add_f32_e32 v88, v88, v89
	ds_read_b128 v[6:9], v0 offset:10240
	ds_read_b128 v[10:13], v0 offset:10496
	ds_read_b128 v[14:17], v0 offset:10752
	ds_read_b128 v[18:21], v0 offset:11008
	v_add_f32_dpp v83, v82, v82 row_mirror row_mask:0xf bank_mask:0xf
	v_add_f32_dpp v83, v84, v84 row_mirror row_mask:0xf bank_mask:0xc
	v_add_f32_dpp v85, v86, v86 row_mirror row_mask:0xf bank_mask:0xf
	v_add_f32_dpp v85, v88, v88 row_mirror row_mask:0xf bank_mask:0xc
	v_add_f32_dpp v87, v83, v83 row_half_mirror row_mask:0xf bank_mask:0xf
	v_pk_fma_f32 v[138:139], v[50:51], v[72:73], v[138:139] op_sel_hi:[1,0,1]
	v_pk_fma_f32 v[140:141], v[52:53], v[72:73], v[140:141] op_sel_hi:[1,0,1]
	v_add_f32_dpp v87, v85, v85 row_half_mirror row_mask:0xf bank_mask:0xa
	v_pk_fma_f32 v[138:139], v[58:59], v[72:73], v[138:139] op_sel:[0,1,0] op_sel_hi:[1,1,1]
	v_pk_fma_f32 v[140:141], v[60:61], v[72:73], v[140:141] op_sel:[0,1,0] op_sel_hi:[1,1,1]
	v_add_f32_dpp v87, v87, v87 quad_perm:[1,0,3,2] row_mask:0xf bank_mask:0xf
	v_mul_f32_e32 v134, s89, v72
	v_mul_f32_e32 v135, s95, v72
	v_add_f32_dpp v87, v87, v87 quad_perm:[2,3,0,1] row_mask:0xf bank_mask:0xf
	v_fmac_f32_e32 v135, s93, v73
	v_mul_f32_e32 v92, s91, v72
	v_mov_b32_dpp v90, v87 row_newbcast:0 row_mask:0xf bank_mask:0xf
	v_add_f32_dpp v92, v87, v92 row_newbcast:4 row_mask:0xf bank_mask:0xf
	v_add_f32_dpp v91, v87, v134 row_newbcast:8 row_mask:0xf bank_mask:0xf
	v_pk_fma_f32 v[138:139], v[46:47], v[90:91], v[138:139] op_sel_hi:[1,0,1] neg_lo:[0,1,0] neg_hi:[0,1,0]
	v_fma_f32 v92, -v90, s90, v92
	v_pk_fma_f32 v[140:141], v[48:49], v[90:91], v[140:141] op_sel_hi:[1,0,1] neg_lo:[0,1,0] neg_hi:[0,1,0]
	v_add_f32_dpp v93, v87, v135 row_newbcast:12 row_mask:0xf bank_mask:0xf
	v_pk_fma_f32 v[138:139], v[54:55], v[92:93], v[138:139] op_sel_hi:[1,0,1] neg_lo:[0,1,0] neg_hi:[0,1,0]
	v_pk_fma_f32 v[140:141], v[56:57], v[92:93], v[140:141] op_sel_hi:[1,0,1] neg_lo:[0,1,0] neg_hi:[0,1,0]
	s_waitcnt lgkmcnt(0)
	s_load_dwordx8 s[76:83], s[96:97], 0x80
	v_pk_mul_f32 v[82:83], v[138:139], v[6:7]
	v_fma_f32 v91, -v90, s88, v91
	v_pk_mul_f32 v[84:85], v[138:139], v[10:11]
	v_fma_f32 v93, -v90, s94, v93
	v_pk_mul_f32 v[86:87], v[138:139], v[14:15]
	v_fma_f32 v93, -v92, s92, v93
	v_pk_mul_f32 v[88:89], v[138:139], v[18:19]
	ds_write2_b32 v159, v91, v93 offset0:32 offset1:48
	v_pk_fma_f32 v[82:83], v[140:141], v[8:9], v[82:83]
	ds_read_b128 v[42:45], v0 offset:14336
	v_pk_fma_f32 v[84:85], v[140:141], v[12:13], v[84:85]
	ds_read_b128 v[46:49], v0 offset:14592
	v_pk_fma_f32 v[86:87], v[140:141], v[16:17], v[86:87]
	ds_read_b128 v[50:53], v0 offset:14848
	v_pk_fma_f32 v[88:89], v[140:141], v[20:21], v[88:89]
	ds_read_b128 v[54:57], v0 offset:15104
	v_pk_mul_f32 v[138:139], v[138:139], v[22:23]
	ds_read_b128 v[58:61], v0 offset:15360
	v_pk_mul_f32 v[140:141], v[140:141], v[24:25]
	ds_read2st64_b32 v[72:73], v158 offset0:61 offset1:62
	v_add_f32_e32 v82, v82, v83
	v_add_f32_e32 v84, v84, v85
	v_add_f32_e32 v86, v86, v87
	v_add_f32_e32 v88, v88, v89
	ds_read_b128 v[6:9], v0 offset:13312
	ds_read_b128 v[10:13], v0 offset:13568
	ds_read_b128 v[14:17], v0 offset:13824
	ds_read_b128 v[18:21], v0 offset:14080
	v_add_f32_dpp v83, v82, v82 row_mirror row_mask:0xf bank_mask:0xf
	v_add_f32_dpp v83, v84, v84 row_mirror row_mask:0xf bank_mask:0xc
	v_add_f32_dpp v85, v86, v86 row_mirror row_mask:0xf bank_mask:0xf
	v_add_f32_dpp v85, v88, v88 row_mirror row_mask:0xf bank_mask:0xc
	v_add_f32_dpp v87, v83, v83 row_half_mirror row_mask:0xf bank_mask:0xf
	v_pk_fma_f32 v[138:139], v[30:31], v[62:63], v[138:139] op_sel_hi:[1,0,1]
	v_pk_fma_f32 v[140:141], v[32:33], v[62:63], v[140:141] op_sel_hi:[1,0,1]
	v_add_f32_dpp v87, v85, v85 row_half_mirror row_mask:0xf bank_mask:0xa
	v_pk_fma_f32 v[138:139], v[38:39], v[62:63], v[138:139] op_sel:[0,1,0] op_sel_hi:[1,1,1]
	v_pk_fma_f32 v[140:141], v[40:41], v[62:63], v[140:141] op_sel:[0,1,0] op_sel_hi:[1,1,1]
	v_add_f32_dpp v87, v87, v87 quad_perm:[1,0,3,2] row_mask:0xf bank_mask:0xf
	v_mul_f32_e32 v134, s29, v62
	v_mul_f32_e32 v135, s35, v62
	v_add_f32_dpp v87, v87, v87 quad_perm:[2,3,0,1] row_mask:0xf bank_mask:0xf
	v_fmac_f32_e32 v135, s33, v63
	v_mul_f32_e32 v92, s31, v62
	v_mov_b32_dpp v90, v87 row_newbcast:0 row_mask:0xf bank_mask:0xf
	v_add_f32_dpp v92, v87, v92 row_newbcast:4 row_mask:0xf bank_mask:0xf
	v_add_f32_dpp v91, v87, v134 row_newbcast:8 row_mask:0xf bank_mask:0xf
	v_pk_fma_f32 v[138:139], v[26:27], v[90:91], v[138:139] op_sel_hi:[1,0,1] neg_lo:[0,1,0] neg_hi:[0,1,0]
	v_fma_f32 v92, -v90, s30, v92
	v_pk_fma_f32 v[140:141], v[28:29], v[90:91], v[140:141] op_sel_hi:[1,0,1] neg_lo:[0,1,0] neg_hi:[0,1,0]
	v_add_f32_dpp v93, v87, v135 row_newbcast:12 row_mask:0xf bank_mask:0xf
	v_pk_fma_f32 v[138:139], v[34:35], v[92:93], v[138:139] op_sel_hi:[1,0,1] neg_lo:[0,1,0] neg_hi:[0,1,0]
	v_pk_fma_f32 v[140:141], v[36:37], v[92:93], v[140:141] op_sel_hi:[1,0,1] neg_lo:[0,1,0] neg_hi:[0,1,0]
	s_waitcnt lgkmcnt(0)
	s_load_dwordx8 s[88:95], s[96:97], 0xa0
	v_pk_mul_f32 v[82:83], v[138:139], v[6:7]
	v_fma_f32 v91, -v90, s28, v91
	v_pk_mul_f32 v[84:85], v[138:139], v[10:11]
	v_fma_f32 v93, -v90, s34, v93
	v_pk_mul_f32 v[86:87], v[138:139], v[14:15]
	v_fma_f32 v93, -v92, s32, v93
	v_pk_mul_f32 v[88:89], v[138:139], v[18:19]
	ds_write2_b32 v159, v91, v93 offset0:64 offset1:80
	v_pk_fma_f32 v[82:83], v[140:141], v[8:9], v[82:83]
	ds_read_b128 v[22:25], v0 offset:17408
	v_pk_fma_f32 v[84:85], v[140:141], v[12:13], v[84:85]
	ds_read_b128 v[26:29], v0 offset:17664
	v_pk_fma_f32 v[86:87], v[140:141], v[16:17], v[86:87]
	ds_read_b128 v[30:33], v0 offset:17920
	v_pk_fma_f32 v[88:89], v[140:141], v[20:21], v[88:89]
	ds_read_b128 v[34:37], v0 offset:18176
	v_pk_mul_f32 v[138:139], v[138:139], v[42:43]
	ds_read_b128 v[38:41], v0 offset:18432
	v_pk_mul_f32 v[140:141], v[140:141], v[44:45]
	ds_read2st64_b32 v[62:63], v158 offset0:73 offset1:74
	v_add_f32_e32 v82, v82, v83
	v_add_f32_e32 v84, v84, v85
	v_add_f32_e32 v86, v86, v87
	v_add_f32_e32 v88, v88, v89
	ds_read_b128 v[6:9], v0 offset:16384
	ds_read_b128 v[10:13], v0 offset:16640
	ds_read_b128 v[14:17], v0 offset:16896
	ds_read_b128 v[18:21], v0 offset:17152
	v_add_f32_dpp v83, v82, v82 row_mirror row_mask:0xf bank_mask:0xf
	v_add_f32_dpp v83, v84, v84 row_mirror row_mask:0xf bank_mask:0xc
	v_add_f32_dpp v85, v86, v86 row_mirror row_mask:0xf bank_mask:0xf
	v_add_f32_dpp v85, v88, v88 row_mirror row_mask:0xf bank_mask:0xc
	v_add_f32_dpp v87, v83, v83 row_half_mirror row_mask:0xf bank_mask:0xf
	v_pk_fma_f32 v[138:139], v[50:51], v[72:73], v[138:139] op_sel_hi:[1,0,1]
	v_pk_fma_f32 v[140:141], v[52:53], v[72:73], v[140:141] op_sel_hi:[1,0,1]
	v_add_f32_dpp v87, v85, v85 row_half_mirror row_mask:0xf bank_mask:0xa
	v_pk_fma_f32 v[138:139], v[58:59], v[72:73], v[138:139] op_sel:[0,1,0] op_sel_hi:[1,1,1]
	v_pk_fma_f32 v[140:141], v[60:61], v[72:73], v[140:141] op_sel:[0,1,0] op_sel_hi:[1,1,1]
	v_add_f32_dpp v87, v87, v87 quad_perm:[1,0,3,2] row_mask:0xf bank_mask:0xf
	v_mul_f32_e32 v134, s5, v72
	v_mul_f32_e32 v135, s11, v72
	v_add_f32_dpp v87, v87, v87 quad_perm:[2,3,0,1] row_mask:0xf bank_mask:0xf
	v_fmac_f32_e32 v135, s9, v73
	v_mul_f32_e32 v92, s7, v72
	v_mov_b32_dpp v90, v87 row_newbcast:0 row_mask:0xf bank_mask:0xf
	v_add_f32_dpp v92, v87, v92 row_newbcast:4 row_mask:0xf bank_mask:0xf
	v_add_f32_dpp v91, v87, v134 row_newbcast:8 row_mask:0xf bank_mask:0xf
	v_pk_fma_f32 v[138:139], v[46:47], v[90:91], v[138:139] op_sel_hi:[1,0,1] neg_lo:[0,1,0] neg_hi:[0,1,0]
	v_fma_f32 v92, -v90, s6, v92
	v_pk_fma_f32 v[140:141], v[48:49], v[90:91], v[140:141] op_sel_hi:[1,0,1] neg_lo:[0,1,0] neg_hi:[0,1,0]
	v_add_f32_dpp v93, v87, v135 row_newbcast:12 row_mask:0xf bank_mask:0xf
	v_pk_fma_f32 v[138:139], v[54:55], v[92:93], v[138:139] op_sel_hi:[1,0,1] neg_lo:[0,1,0] neg_hi:[0,1,0]
	v_pk_fma_f32 v[140:141], v[56:57], v[92:93], v[140:141] op_sel_hi:[1,0,1] neg_lo:[0,1,0] neg_hi:[0,1,0]
	s_waitcnt lgkmcnt(0)
	s_load_dwordx8 s[28:35], s[96:97], 0xc0
	v_pk_mul_f32 v[82:83], v[138:139], v[6:7]
	v_fma_f32 v91, -v90, s4, v91
	v_pk_mul_f32 v[84:85], v[138:139], v[10:11]
	v_fma_f32 v93, -v90, s10, v93
	v_pk_mul_f32 v[86:87], v[138:139], v[14:15]
	v_fma_f32 v93, -v92, s8, v93
	v_pk_mul_f32 v[88:89], v[138:139], v[18:19]
	ds_write2_b32 v159, v91, v93 offset0:96 offset1:112
	v_pk_fma_f32 v[82:83], v[140:141], v[8:9], v[82:83]
	ds_read_b128 v[42:45], v0 offset:20480
	v_pk_fma_f32 v[84:85], v[140:141], v[12:13], v[84:85]
	ds_read_b128 v[46:49], v0 offset:20736
	v_pk_fma_f32 v[86:87], v[140:141], v[16:17], v[86:87]
	ds_read_b128 v[50:53], v0 offset:20992
	v_pk_fma_f32 v[88:89], v[140:141], v[20:21], v[88:89]
	ds_read_b128 v[54:57], v0 offset:21248
	v_pk_mul_f32 v[138:139], v[138:139], v[22:23]
	ds_read_b128 v[58:61], v0 offset:21504
	v_pk_mul_f32 v[140:141], v[140:141], v[24:25]
	ds_read2st64_b32 v[72:73], v158 offset0:85 offset1:86
	v_add_f32_e32 v82, v82, v83
	v_add_f32_e32 v84, v84, v85
	v_add_f32_e32 v86, v86, v87
	v_add_f32_e32 v88, v88, v89
	ds_read_b128 v[6:9], v0 offset:19456
	ds_read_b128 v[10:13], v0 offset:19712
	ds_read_b128 v[14:17], v0 offset:19968
	ds_read_b128 v[18:21], v0 offset:20224
	v_add_f32_dpp v83, v82, v82 row_mirror row_mask:0xf bank_mask:0xf
	v_add_f32_dpp v83, v84, v84 row_mirror row_mask:0xf bank_mask:0xc
	v_add_f32_dpp v85, v86, v86 row_mirror row_mask:0xf bank_mask:0xf
	v_add_f32_dpp v85, v88, v88 row_mirror row_mask:0xf bank_mask:0xc
	v_add_f32_dpp v87, v83, v83 row_half_mirror row_mask:0xf bank_mask:0xf
	v_pk_fma_f32 v[138:139], v[30:31], v[62:63], v[138:139] op_sel_hi:[1,0,1]
	v_pk_fma_f32 v[140:141], v[32:33], v[62:63], v[140:141] op_sel_hi:[1,0,1]
	v_add_f32_dpp v87, v85, v85 row_half_mirror row_mask:0xf bank_mask:0xa
	v_pk_fma_f32 v[138:139], v[38:39], v[62:63], v[138:139] op_sel:[0,1,0] op_sel_hi:[1,1,1]
	v_pk_fma_f32 v[140:141], v[40:41], v[62:63], v[140:141] op_sel:[0,1,0] op_sel_hi:[1,1,1]
	v_add_f32_dpp v87, v87, v87 quad_perm:[1,0,3,2] row_mask:0xf bank_mask:0xf
	v_mul_f32_e32 v134, s77, v62
	v_mul_f32_e32 v135, s83, v62
	v_add_f32_dpp v87, v87, v87 quad_perm:[2,3,0,1] row_mask:0xf bank_mask:0xf
	v_fmac_f32_e32 v135, s81, v63
	v_mul_f32_e32 v92, s79, v62
	v_mov_b32_dpp v90, v87 row_newbcast:0 row_mask:0xf bank_mask:0xf
	v_add_f32_dpp v92, v87, v92 row_newbcast:4 row_mask:0xf bank_mask:0xf
	v_add_f32_dpp v91, v87, v134 row_newbcast:8 row_mask:0xf bank_mask:0xf
	v_pk_fma_f32 v[138:139], v[26:27], v[90:91], v[138:139] op_sel_hi:[1,0,1] neg_lo:[0,1,0] neg_hi:[0,1,0]
	v_fma_f32 v92, -v90, s78, v92
	v_pk_fma_f32 v[140:141], v[28:29], v[90:91], v[140:141] op_sel_hi:[1,0,1] neg_lo:[0,1,0] neg_hi:[0,1,0]
	v_add_f32_dpp v93, v87, v135 row_newbcast:12 row_mask:0xf bank_mask:0xf
	v_pk_fma_f32 v[138:139], v[34:35], v[92:93], v[138:139] op_sel_hi:[1,0,1] neg_lo:[0,1,0] neg_hi:[0,1,0]
	v_pk_fma_f32 v[140:141], v[36:37], v[92:93], v[140:141] op_sel_hi:[1,0,1] neg_lo:[0,1,0] neg_hi:[0,1,0]
	s_waitcnt lgkmcnt(0)
	s_load_dwordx8 s[4:11], s[96:97], 0xe0
	v_pk_mul_f32 v[82:83], v[138:139], v[6:7]
	v_fma_f32 v91, -v90, s76, v91
	v_pk_mul_f32 v[84:85], v[138:139], v[10:11]
	v_fma_f32 v93, -v90, s82, v93
	v_pk_mul_f32 v[86:87], v[138:139], v[14:15]
	v_fma_f32 v93, -v92, s80, v93
	v_pk_mul_f32 v[88:89], v[138:139], v[18:19]
	ds_write2_b32 v159, v91, v93 offset0:128 offset1:144
	v_pk_fma_f32 v[82:83], v[140:141], v[8:9], v[82:83]
	ds_read_b128 v[22:25], v0 offset:23552
	v_pk_fma_f32 v[84:85], v[140:141], v[12:13], v[84:85]
	ds_read_b128 v[26:29], v0 offset:23808
	v_pk_fma_f32 v[86:87], v[140:141], v[16:17], v[86:87]
	ds_read_b128 v[30:33], v0 offset:24064
	v_pk_fma_f32 v[88:89], v[140:141], v[20:21], v[88:89]
	ds_read_b128 v[34:37], v0 offset:24320
	v_pk_mul_f32 v[138:139], v[138:139], v[42:43]
	ds_read_b128 v[38:41], v0 offset:24576
	v_pk_mul_f32 v[140:141], v[140:141], v[44:45]
	ds_read2st64_b32 v[62:63], v158 offset0:97 offset1:98
	v_add_f32_e32 v82, v82, v83
	v_add_f32_e32 v84, v84, v85
	v_add_f32_e32 v86, v86, v87
	v_add_f32_e32 v88, v88, v89
	ds_read_b128 v[6:9], v0 offset:22528
	ds_read_b128 v[10:13], v0 offset:22784
	ds_read_b128 v[14:17], v0 offset:23040
	ds_read_b128 v[18:21], v0 offset:23296
	v_add_f32_dpp v83, v82, v82 row_mirror row_mask:0xf bank_mask:0xf
	v_add_f32_dpp v83, v84, v84 row_mirror row_mask:0xf bank_mask:0xc
	v_add_f32_dpp v85, v86, v86 row_mirror row_mask:0xf bank_mask:0xf
	v_add_f32_dpp v85, v88, v88 row_mirror row_mask:0xf bank_mask:0xc
	v_add_f32_dpp v87, v83, v83 row_half_mirror row_mask:0xf bank_mask:0xf
	v_pk_fma_f32 v[138:139], v[50:51], v[72:73], v[138:139] op_sel_hi:[1,0,1]
	v_pk_fma_f32 v[140:141], v[52:53], v[72:73], v[140:141] op_sel_hi:[1,0,1]
	v_add_f32_dpp v87, v85, v85 row_half_mirror row_mask:0xf bank_mask:0xa
	v_pk_fma_f32 v[138:139], v[58:59], v[72:73], v[138:139] op_sel:[0,1,0] op_sel_hi:[1,1,1]
	v_pk_fma_f32 v[140:141], v[60:61], v[72:73], v[140:141] op_sel:[0,1,0] op_sel_hi:[1,1,1]
	v_add_f32_dpp v87, v87, v87 quad_perm:[1,0,3,2] row_mask:0xf bank_mask:0xf
	v_mul_f32_e32 v134, s89, v72
	v_mul_f32_e32 v135, s95, v72
	v_add_f32_dpp v87, v87, v87 quad_perm:[2,3,0,1] row_mask:0xf bank_mask:0xf
	v_fmac_f32_e32 v135, s93, v73
	v_mul_f32_e32 v92, s91, v72
	v_mov_b32_dpp v90, v87 row_newbcast:0 row_mask:0xf bank_mask:0xf
	v_add_f32_dpp v92, v87, v92 row_newbcast:4 row_mask:0xf bank_mask:0xf
	v_add_f32_dpp v91, v87, v134 row_newbcast:8 row_mask:0xf bank_mask:0xf
	v_pk_fma_f32 v[138:139], v[46:47], v[90:91], v[138:139] op_sel_hi:[1,0,1] neg_lo:[0,1,0] neg_hi:[0,1,0]
	v_fma_f32 v92, -v90, s90, v92
	v_pk_fma_f32 v[140:141], v[48:49], v[90:91], v[140:141] op_sel_hi:[1,0,1] neg_lo:[0,1,0] neg_hi:[0,1,0]
	v_add_f32_dpp v93, v87, v135 row_newbcast:12 row_mask:0xf bank_mask:0xf
	v_pk_fma_f32 v[138:139], v[54:55], v[92:93], v[138:139] op_sel_hi:[1,0,1] neg_lo:[0,1,0] neg_hi:[0,1,0]
	v_pk_fma_f32 v[140:141], v[56:57], v[92:93], v[140:141] op_sel_hi:[1,0,1] neg_lo:[0,1,0] neg_hi:[0,1,0]
	s_waitcnt lgkmcnt(0)
	s_load_dwordx8 s[76:83], s[96:97], 0x100
	v_pk_mul_f32 v[82:83], v[138:139], v[6:7]
	v_fma_f32 v91, -v90, s88, v91
	v_pk_mul_f32 v[84:85], v[138:139], v[10:11]
	v_fma_f32 v93, -v90, s94, v93
	v_pk_mul_f32 v[86:87], v[138:139], v[14:15]
	v_fma_f32 v93, -v92, s92, v93
	v_pk_mul_f32 v[88:89], v[138:139], v[18:19]
	ds_write2_b32 v159, v91, v93 offset0:160 offset1:176
	v_pk_fma_f32 v[82:83], v[140:141], v[8:9], v[82:83]
	ds_read_b128 v[42:45], v0 offset:26624
	v_pk_fma_f32 v[84:85], v[140:141], v[12:13], v[84:85]
	ds_read_b128 v[46:49], v0 offset:26880
	v_pk_fma_f32 v[86:87], v[140:141], v[16:17], v[86:87]
	ds_read_b128 v[50:53], v0 offset:27136
	v_pk_fma_f32 v[88:89], v[140:141], v[20:21], v[88:89]
	ds_read_b128 v[54:57], v0 offset:27392
	v_pk_mul_f32 v[138:139], v[138:139], v[22:23]
	ds_read_b128 v[58:61], v0 offset:27648
	v_pk_mul_f32 v[140:141], v[140:141], v[24:25]
	ds_read2st64_b32 v[72:73], v158 offset0:109 offset1:110
	v_add_f32_e32 v82, v82, v83
	v_add_f32_e32 v84, v84, v85
	v_add_f32_e32 v86, v86, v87
	v_add_f32_e32 v88, v88, v89
	ds_read_b128 v[6:9], v0 offset:25600
	ds_read_b128 v[10:13], v0 offset:25856
	ds_read_b128 v[14:17], v0 offset:26112
	ds_read_b128 v[18:21], v0 offset:26368
	v_add_f32_dpp v83, v82, v82 row_mirror row_mask:0xf bank_mask:0xf
	v_add_f32_dpp v83, v84, v84 row_mirror row_mask:0xf bank_mask:0xc
	v_add_f32_dpp v85, v86, v86 row_mirror row_mask:0xf bank_mask:0xf
	v_add_f32_dpp v85, v88, v88 row_mirror row_mask:0xf bank_mask:0xc
	v_add_f32_dpp v87, v83, v83 row_half_mirror row_mask:0xf bank_mask:0xf
	v_pk_fma_f32 v[138:139], v[30:31], v[62:63], v[138:139] op_sel_hi:[1,0,1]
	v_pk_fma_f32 v[140:141], v[32:33], v[62:63], v[140:141] op_sel_hi:[1,0,1]
	v_add_f32_dpp v87, v85, v85 row_half_mirror row_mask:0xf bank_mask:0xa
	v_pk_fma_f32 v[138:139], v[38:39], v[62:63], v[138:139] op_sel:[0,1,0] op_sel_hi:[1,1,1]
	v_pk_fma_f32 v[140:141], v[40:41], v[62:63], v[140:141] op_sel:[0,1,0] op_sel_hi:[1,1,1]
	v_add_f32_dpp v87, v87, v87 quad_perm:[1,0,3,2] row_mask:0xf bank_mask:0xf
	v_mul_f32_e32 v134, s29, v62
	v_mul_f32_e32 v135, s35, v62
	v_add_f32_dpp v87, v87, v87 quad_perm:[2,3,0,1] row_mask:0xf bank_mask:0xf
	v_fmac_f32_e32 v135, s33, v63
	v_mul_f32_e32 v92, s31, v62
	v_mov_b32_dpp v90, v87 row_newbcast:0 row_mask:0xf bank_mask:0xf
	v_add_f32_dpp v92, v87, v92 row_newbcast:4 row_mask:0xf bank_mask:0xf
	v_add_f32_dpp v91, v87, v134 row_newbcast:8 row_mask:0xf bank_mask:0xf
	v_pk_fma_f32 v[138:139], v[26:27], v[90:91], v[138:139] op_sel_hi:[1,0,1] neg_lo:[0,1,0] neg_hi:[0,1,0]
	v_fma_f32 v92, -v90, s30, v92
	v_pk_fma_f32 v[140:141], v[28:29], v[90:91], v[140:141] op_sel_hi:[1,0,1] neg_lo:[0,1,0] neg_hi:[0,1,0]
	v_add_f32_dpp v93, v87, v135 row_newbcast:12 row_mask:0xf bank_mask:0xf
	v_pk_fma_f32 v[138:139], v[34:35], v[92:93], v[138:139] op_sel_hi:[1,0,1] neg_lo:[0,1,0] neg_hi:[0,1,0]
	v_pk_fma_f32 v[140:141], v[36:37], v[92:93], v[140:141] op_sel_hi:[1,0,1] neg_lo:[0,1,0] neg_hi:[0,1,0]
	s_waitcnt lgkmcnt(0)
	s_load_dwordx8 s[88:95], s[96:97], 0x120
	v_pk_mul_f32 v[82:83], v[138:139], v[6:7]
	v_fma_f32 v91, -v90, s28, v91
	v_pk_mul_f32 v[84:85], v[138:139], v[10:11]
	v_fma_f32 v93, -v90, s34, v93
	v_pk_mul_f32 v[86:87], v[138:139], v[14:15]
	v_fma_f32 v93, -v92, s32, v93
	v_pk_mul_f32 v[88:89], v[138:139], v[18:19]
	ds_write2_b32 v159, v91, v93 offset0:192 offset1:208
	v_pk_fma_f32 v[82:83], v[140:141], v[8:9], v[82:83]
	ds_read_b128 v[22:25], v0 offset:29696
	v_pk_fma_f32 v[84:85], v[140:141], v[12:13], v[84:85]
	ds_read_b128 v[26:29], v0 offset:29952
	v_pk_fma_f32 v[86:87], v[140:141], v[16:17], v[86:87]
	ds_read_b128 v[30:33], v0 offset:30208
	v_pk_fma_f32 v[88:89], v[140:141], v[20:21], v[88:89]
	ds_read_b128 v[34:37], v0 offset:30464
	v_pk_mul_f32 v[138:139], v[138:139], v[42:43]
	ds_read_b128 v[38:41], v0 offset:30720
	v_pk_mul_f32 v[140:141], v[140:141], v[44:45]
	ds_read2st64_b32 v[62:63], v158 offset0:121 offset1:122
	v_add_f32_e32 v82, v82, v83
	v_add_f32_e32 v84, v84, v85
	v_add_f32_e32 v86, v86, v87
	v_add_f32_e32 v88, v88, v89
	ds_read_b128 v[6:9], v0 offset:28672
	ds_read_b128 v[10:13], v0 offset:28928
	ds_read_b128 v[14:17], v0 offset:29184
	ds_read_b128 v[18:21], v0 offset:29440
	v_add_f32_dpp v83, v82, v82 row_mirror row_mask:0xf bank_mask:0xf
	v_add_f32_dpp v83, v84, v84 row_mirror row_mask:0xf bank_mask:0xc
	v_add_f32_dpp v85, v86, v86 row_mirror row_mask:0xf bank_mask:0xf
	v_add_f32_dpp v85, v88, v88 row_mirror row_mask:0xf bank_mask:0xc
	v_add_f32_dpp v87, v83, v83 row_half_mirror row_mask:0xf bank_mask:0xf
	v_pk_fma_f32 v[138:139], v[50:51], v[72:73], v[138:139] op_sel_hi:[1,0,1]
	v_pk_fma_f32 v[140:141], v[52:53], v[72:73], v[140:141] op_sel_hi:[1,0,1]
	v_add_f32_dpp v87, v85, v85 row_half_mirror row_mask:0xf bank_mask:0xa
	v_pk_fma_f32 v[138:139], v[58:59], v[72:73], v[138:139] op_sel:[0,1,0] op_sel_hi:[1,1,1]
	v_pk_fma_f32 v[140:141], v[60:61], v[72:73], v[140:141] op_sel:[0,1,0] op_sel_hi:[1,1,1]
	v_add_f32_dpp v87, v87, v87 quad_perm:[1,0,3,2] row_mask:0xf bank_mask:0xf
	v_mul_f32_e32 v134, s5, v72
	v_mul_f32_e32 v135, s11, v72
	v_add_f32_dpp v87, v87, v87 quad_perm:[2,3,0,1] row_mask:0xf bank_mask:0xf
	v_fmac_f32_e32 v135, s9, v73
	v_mul_f32_e32 v92, s7, v72
	v_mov_b32_dpp v90, v87 row_newbcast:0 row_mask:0xf bank_mask:0xf
	v_add_f32_dpp v92, v87, v92 row_newbcast:4 row_mask:0xf bank_mask:0xf
	v_add_f32_dpp v91, v87, v134 row_newbcast:8 row_mask:0xf bank_mask:0xf
	v_pk_fma_f32 v[138:139], v[46:47], v[90:91], v[138:139] op_sel_hi:[1,0,1] neg_lo:[0,1,0] neg_hi:[0,1,0]
	v_fma_f32 v92, -v90, s6, v92
	v_pk_fma_f32 v[140:141], v[48:49], v[90:91], v[140:141] op_sel_hi:[1,0,1] neg_lo:[0,1,0] neg_hi:[0,1,0]
	v_add_f32_dpp v93, v87, v135 row_newbcast:12 row_mask:0xf bank_mask:0xf
	v_pk_fma_f32 v[138:139], v[54:55], v[92:93], v[138:139] op_sel_hi:[1,0,1] neg_lo:[0,1,0] neg_hi:[0,1,0]
	v_pk_fma_f32 v[140:141], v[56:57], v[92:93], v[140:141] op_sel_hi:[1,0,1] neg_lo:[0,1,0] neg_hi:[0,1,0]
	s_waitcnt lgkmcnt(0)
	s_load_dwordx8 s[28:35], s[96:97], 0x140
	v_pk_mul_f32 v[82:83], v[138:139], v[6:7]
	v_fma_f32 v91, -v90, s4, v91
	v_pk_mul_f32 v[84:85], v[138:139], v[10:11]
	v_fma_f32 v93, -v90, s10, v93
	v_pk_mul_f32 v[86:87], v[138:139], v[14:15]
	v_fma_f32 v93, -v92, s8, v93
	v_pk_mul_f32 v[88:89], v[138:139], v[18:19]
	ds_write2_b32 v159, v91, v93 offset0:224 offset1:240
	v_pk_fma_f32 v[82:83], v[140:141], v[8:9], v[82:83]
	ds_read_b128 v[42:45], v0 offset:32768
	v_pk_fma_f32 v[84:85], v[140:141], v[12:13], v[84:85]
	ds_read_b128 v[46:49], v0 offset:33024
	v_pk_fma_f32 v[86:87], v[140:141], v[16:17], v[86:87]
	ds_read_b128 v[50:53], v0 offset:33280
	v_pk_fma_f32 v[88:89], v[140:141], v[20:21], v[88:89]
	ds_read_b128 v[54:57], v0 offset:33536
	v_pk_mul_f32 v[138:139], v[138:139], v[22:23]
	ds_read_b128 v[58:61], v0 offset:33792
	v_pk_mul_f32 v[140:141], v[140:141], v[24:25]
	ds_read2st64_b32 v[72:73], v158 offset0:133 offset1:134
	v_add_f32_e32 v82, v82, v83
	v_add_f32_e32 v84, v84, v85
	v_add_f32_e32 v86, v86, v87
	v_add_f32_e32 v88, v88, v89
	ds_read_b128 v[6:9], v0 offset:31744
	ds_read_b128 v[10:13], v0 offset:32000
	ds_read_b128 v[14:17], v0 offset:32256
	ds_read_b128 v[18:21], v0 offset:32512
	v_add_f32_dpp v83, v82, v82 row_mirror row_mask:0xf bank_mask:0xf
	v_add_f32_dpp v83, v84, v84 row_mirror row_mask:0xf bank_mask:0xc
	v_add_f32_dpp v85, v86, v86 row_mirror row_mask:0xf bank_mask:0xf
	v_add_f32_dpp v85, v88, v88 row_mirror row_mask:0xf bank_mask:0xc
	v_add_f32_dpp v87, v83, v83 row_half_mirror row_mask:0xf bank_mask:0xf
	v_pk_fma_f32 v[138:139], v[30:31], v[62:63], v[138:139] op_sel_hi:[1,0,1]
	v_pk_fma_f32 v[140:141], v[32:33], v[62:63], v[140:141] op_sel_hi:[1,0,1]
	v_add_f32_dpp v87, v85, v85 row_half_mirror row_mask:0xf bank_mask:0xa
	v_pk_fma_f32 v[138:139], v[38:39], v[62:63], v[138:139] op_sel:[0,1,0] op_sel_hi:[1,1,1]
	v_pk_fma_f32 v[140:141], v[40:41], v[62:63], v[140:141] op_sel:[0,1,0] op_sel_hi:[1,1,1]
	v_add_f32_dpp v87, v87, v87 quad_perm:[1,0,3,2] row_mask:0xf bank_mask:0xf
	v_mul_f32_e32 v134, s77, v62
	v_mul_f32_e32 v135, s83, v62
	v_add_f32_dpp v87, v87, v87 quad_perm:[2,3,0,1] row_mask:0xf bank_mask:0xf
	v_fmac_f32_e32 v135, s81, v63
	v_mul_f32_e32 v92, s79, v62
	v_mov_b32_dpp v90, v87 row_newbcast:0 row_mask:0xf bank_mask:0xf
	v_add_f32_dpp v92, v87, v92 row_newbcast:4 row_mask:0xf bank_mask:0xf
	v_add_f32_dpp v91, v87, v134 row_newbcast:8 row_mask:0xf bank_mask:0xf
	v_pk_fma_f32 v[138:139], v[26:27], v[90:91], v[138:139] op_sel_hi:[1,0,1] neg_lo:[0,1,0] neg_hi:[0,1,0]
	v_fma_f32 v92, -v90, s78, v92
	v_pk_fma_f32 v[140:141], v[28:29], v[90:91], v[140:141] op_sel_hi:[1,0,1] neg_lo:[0,1,0] neg_hi:[0,1,0]
	v_add_f32_dpp v93, v87, v135 row_newbcast:12 row_mask:0xf bank_mask:0xf
	v_pk_fma_f32 v[138:139], v[34:35], v[92:93], v[138:139] op_sel_hi:[1,0,1] neg_lo:[0,1,0] neg_hi:[0,1,0]
	v_pk_fma_f32 v[140:141], v[36:37], v[92:93], v[140:141] op_sel_hi:[1,0,1] neg_lo:[0,1,0] neg_hi:[0,1,0]
	s_waitcnt lgkmcnt(0)
	s_load_dwordx8 s[4:11], s[96:97], 0x160
	v_pk_mul_f32 v[82:83], v[138:139], v[6:7]
	v_fma_f32 v91, -v90, s76, v91
	v_pk_mul_f32 v[84:85], v[138:139], v[10:11]
	v_fma_f32 v93, -v90, s82, v93
	v_pk_mul_f32 v[86:87], v[138:139], v[14:15]
	v_fma_f32 v93, -v92, s80, v93
	v_pk_mul_f32 v[88:89], v[138:139], v[18:19]
	ds_write2_b32 v166, v91, v93 offset0:0 offset1:16
	v_pk_fma_f32 v[82:83], v[140:141], v[8:9], v[82:83]
	ds_read_b128 v[22:25], v0 offset:35840
	v_pk_fma_f32 v[84:85], v[140:141], v[12:13], v[84:85]
	ds_read_b128 v[26:29], v0 offset:36096
	v_pk_fma_f32 v[86:87], v[140:141], v[16:17], v[86:87]
	ds_read_b128 v[30:33], v0 offset:36352
	v_pk_fma_f32 v[88:89], v[140:141], v[20:21], v[88:89]
	ds_read_b128 v[34:37], v0 offset:36608
	v_pk_mul_f32 v[138:139], v[138:139], v[42:43]
	ds_read_b128 v[38:41], v0 offset:36864
	v_pk_mul_f32 v[140:141], v[140:141], v[44:45]
	ds_read2st64_b32 v[62:63], v158 offset0:145 offset1:146
	v_add_f32_e32 v82, v82, v83
	v_add_f32_e32 v84, v84, v85
	v_add_f32_e32 v86, v86, v87
	v_add_f32_e32 v88, v88, v89
	ds_read_b128 v[6:9], v0 offset:34816
	ds_read_b128 v[10:13], v0 offset:35072
	ds_read_b128 v[14:17], v0 offset:35328
	ds_read_b128 v[18:21], v0 offset:35584
	v_add_f32_dpp v83, v82, v82 row_mirror row_mask:0xf bank_mask:0xf
	v_add_f32_dpp v83, v84, v84 row_mirror row_mask:0xf bank_mask:0xc
	v_add_f32_dpp v85, v86, v86 row_mirror row_mask:0xf bank_mask:0xf
	v_add_f32_dpp v85, v88, v88 row_mirror row_mask:0xf bank_mask:0xc
	v_add_f32_dpp v87, v83, v83 row_half_mirror row_mask:0xf bank_mask:0xf
	v_pk_fma_f32 v[138:139], v[50:51], v[72:73], v[138:139] op_sel_hi:[1,0,1]
	v_pk_fma_f32 v[140:141], v[52:53], v[72:73], v[140:141] op_sel_hi:[1,0,1]
	v_add_f32_dpp v87, v85, v85 row_half_mirror row_mask:0xf bank_mask:0xa
	v_pk_fma_f32 v[138:139], v[58:59], v[72:73], v[138:139] op_sel:[0,1,0] op_sel_hi:[1,1,1]
	v_pk_fma_f32 v[140:141], v[60:61], v[72:73], v[140:141] op_sel:[0,1,0] op_sel_hi:[1,1,1]
	v_add_f32_dpp v87, v87, v87 quad_perm:[1,0,3,2] row_mask:0xf bank_mask:0xf
	v_mul_f32_e32 v134, s89, v72
	v_mul_f32_e32 v135, s95, v72
	v_add_f32_dpp v87, v87, v87 quad_perm:[2,3,0,1] row_mask:0xf bank_mask:0xf
	v_fmac_f32_e32 v135, s93, v73
	v_mul_f32_e32 v92, s91, v72
	v_mov_b32_dpp v90, v87 row_newbcast:0 row_mask:0xf bank_mask:0xf
	v_add_f32_dpp v92, v87, v92 row_newbcast:4 row_mask:0xf bank_mask:0xf
	v_add_f32_dpp v91, v87, v134 row_newbcast:8 row_mask:0xf bank_mask:0xf
	v_pk_fma_f32 v[138:139], v[46:47], v[90:91], v[138:139] op_sel_hi:[1,0,1] neg_lo:[0,1,0] neg_hi:[0,1,0]
	v_fma_f32 v92, -v90, s90, v92
	v_pk_fma_f32 v[140:141], v[48:49], v[90:91], v[140:141] op_sel_hi:[1,0,1] neg_lo:[0,1,0] neg_hi:[0,1,0]
	v_add_f32_dpp v93, v87, v135 row_newbcast:12 row_mask:0xf bank_mask:0xf
	v_pk_fma_f32 v[138:139], v[54:55], v[92:93], v[138:139] op_sel_hi:[1,0,1] neg_lo:[0,1,0] neg_hi:[0,1,0]
	v_pk_fma_f32 v[140:141], v[56:57], v[92:93], v[140:141] op_sel_hi:[1,0,1] neg_lo:[0,1,0] neg_hi:[0,1,0]
	s_waitcnt lgkmcnt(0)
	s_load_dwordx8 s[76:83], s[96:97], 0x180
	v_pk_mul_f32 v[82:83], v[138:139], v[6:7]
	v_fma_f32 v91, -v90, s88, v91
	v_pk_mul_f32 v[84:85], v[138:139], v[10:11]
	v_fma_f32 v93, -v90, s94, v93
	v_pk_mul_f32 v[86:87], v[138:139], v[14:15]
	v_fma_f32 v93, -v92, s92, v93
	v_pk_mul_f32 v[88:89], v[138:139], v[18:19]
	ds_write2_b32 v166, v91, v93 offset0:32 offset1:48
	v_pk_fma_f32 v[82:83], v[140:141], v[8:9], v[82:83]
	ds_read_b128 v[42:45], v0 offset:38912
	v_pk_fma_f32 v[84:85], v[140:141], v[12:13], v[84:85]
	ds_read_b128 v[46:49], v0 offset:39168
	v_pk_fma_f32 v[86:87], v[140:141], v[16:17], v[86:87]
	ds_read_b128 v[50:53], v0 offset:39424
	v_pk_fma_f32 v[88:89], v[140:141], v[20:21], v[88:89]
	ds_read_b128 v[54:57], v0 offset:39680
	v_pk_mul_f32 v[138:139], v[138:139], v[22:23]
	ds_read_b128 v[58:61], v0 offset:39936
	v_pk_mul_f32 v[140:141], v[140:141], v[24:25]
	ds_read2st64_b32 v[72:73], v158 offset0:157 offset1:158
	v_add_f32_e32 v82, v82, v83
	v_add_f32_e32 v84, v84, v85
	v_add_f32_e32 v86, v86, v87
	v_add_f32_e32 v88, v88, v89
	ds_read_b128 v[6:9], v0 offset:37888
	ds_read_b128 v[10:13], v0 offset:38144
	ds_read_b128 v[14:17], v0 offset:38400
	ds_read_b128 v[18:21], v0 offset:38656
	v_add_f32_dpp v83, v82, v82 row_mirror row_mask:0xf bank_mask:0xf
	v_add_f32_dpp v83, v84, v84 row_mirror row_mask:0xf bank_mask:0xc
	v_add_f32_dpp v85, v86, v86 row_mirror row_mask:0xf bank_mask:0xf
	v_add_f32_dpp v85, v88, v88 row_mirror row_mask:0xf bank_mask:0xc
	v_add_f32_dpp v87, v83, v83 row_half_mirror row_mask:0xf bank_mask:0xf
	v_pk_fma_f32 v[138:139], v[30:31], v[62:63], v[138:139] op_sel_hi:[1,0,1]
	v_pk_fma_f32 v[140:141], v[32:33], v[62:63], v[140:141] op_sel_hi:[1,0,1]
	v_add_f32_dpp v87, v85, v85 row_half_mirror row_mask:0xf bank_mask:0xa
	v_pk_fma_f32 v[138:139], v[38:39], v[62:63], v[138:139] op_sel:[0,1,0] op_sel_hi:[1,1,1]
	v_pk_fma_f32 v[140:141], v[40:41], v[62:63], v[140:141] op_sel:[0,1,0] op_sel_hi:[1,1,1]
	v_add_f32_dpp v87, v87, v87 quad_perm:[1,0,3,2] row_mask:0xf bank_mask:0xf
	v_mul_f32_e32 v134, s29, v62
	v_mul_f32_e32 v135, s35, v62
	v_add_f32_dpp v87, v87, v87 quad_perm:[2,3,0,1] row_mask:0xf bank_mask:0xf
	v_fmac_f32_e32 v135, s33, v63
	v_mul_f32_e32 v92, s31, v62
	v_mov_b32_dpp v90, v87 row_newbcast:0 row_mask:0xf bank_mask:0xf
	v_add_f32_dpp v92, v87, v92 row_newbcast:4 row_mask:0xf bank_mask:0xf
	v_add_f32_dpp v91, v87, v134 row_newbcast:8 row_mask:0xf bank_mask:0xf
	v_pk_fma_f32 v[138:139], v[26:27], v[90:91], v[138:139] op_sel_hi:[1,0,1] neg_lo:[0,1,0] neg_hi:[0,1,0]
	v_fma_f32 v92, -v90, s30, v92
	v_pk_fma_f32 v[140:141], v[28:29], v[90:91], v[140:141] op_sel_hi:[1,0,1] neg_lo:[0,1,0] neg_hi:[0,1,0]
	v_add_f32_dpp v93, v87, v135 row_newbcast:12 row_mask:0xf bank_mask:0xf
	v_pk_fma_f32 v[138:139], v[34:35], v[92:93], v[138:139] op_sel_hi:[1,0,1] neg_lo:[0,1,0] neg_hi:[0,1,0]
	v_pk_fma_f32 v[140:141], v[36:37], v[92:93], v[140:141] op_sel_hi:[1,0,1] neg_lo:[0,1,0] neg_hi:[0,1,0]
	s_waitcnt lgkmcnt(0)
	s_load_dwordx8 s[88:95], s[96:97], 0x1a0
	v_pk_mul_f32 v[82:83], v[138:139], v[6:7]
	v_fma_f32 v91, -v90, s28, v91
	v_pk_mul_f32 v[84:85], v[138:139], v[10:11]
	v_fma_f32 v93, -v90, s34, v93
	v_pk_mul_f32 v[86:87], v[138:139], v[14:15]
	v_fma_f32 v93, -v92, s32, v93
	v_pk_mul_f32 v[88:89], v[138:139], v[18:19]
	ds_write2_b32 v166, v91, v93 offset0:64 offset1:80
	v_pk_fma_f32 v[82:83], v[140:141], v[8:9], v[82:83]
	ds_read_b128 v[22:25], v0 offset:41984
	v_pk_fma_f32 v[84:85], v[140:141], v[12:13], v[84:85]
	ds_read_b128 v[26:29], v0 offset:42240
	v_pk_fma_f32 v[86:87], v[140:141], v[16:17], v[86:87]
	ds_read_b128 v[30:33], v0 offset:42496
	v_pk_fma_f32 v[88:89], v[140:141], v[20:21], v[88:89]
	ds_read_b128 v[34:37], v0 offset:42752
	v_pk_mul_f32 v[138:139], v[138:139], v[42:43]
	ds_read_b128 v[38:41], v0 offset:43008
	v_pk_mul_f32 v[140:141], v[140:141], v[44:45]
	ds_read2st64_b32 v[62:63], v158 offset0:169 offset1:170
	v_add_f32_e32 v82, v82, v83
	v_add_f32_e32 v84, v84, v85
	v_add_f32_e32 v86, v86, v87
	v_add_f32_e32 v88, v88, v89
	ds_read_b128 v[6:9], v0 offset:40960
	ds_read_b128 v[10:13], v0 offset:41216
	ds_read_b128 v[14:17], v0 offset:41472
	ds_read_b128 v[18:21], v0 offset:41728
	v_add_f32_dpp v83, v82, v82 row_mirror row_mask:0xf bank_mask:0xf
	v_add_f32_dpp v83, v84, v84 row_mirror row_mask:0xf bank_mask:0xc
	v_add_f32_dpp v85, v86, v86 row_mirror row_mask:0xf bank_mask:0xf
	v_add_f32_dpp v85, v88, v88 row_mirror row_mask:0xf bank_mask:0xc
	v_add_f32_dpp v87, v83, v83 row_half_mirror row_mask:0xf bank_mask:0xf
	v_pk_fma_f32 v[138:139], v[50:51], v[72:73], v[138:139] op_sel_hi:[1,0,1]
	v_pk_fma_f32 v[140:141], v[52:53], v[72:73], v[140:141] op_sel_hi:[1,0,1]
	v_add_f32_dpp v87, v85, v85 row_half_mirror row_mask:0xf bank_mask:0xa
	v_pk_fma_f32 v[138:139], v[58:59], v[72:73], v[138:139] op_sel:[0,1,0] op_sel_hi:[1,1,1]
	v_pk_fma_f32 v[140:141], v[60:61], v[72:73], v[140:141] op_sel:[0,1,0] op_sel_hi:[1,1,1]
	v_add_f32_dpp v87, v87, v87 quad_perm:[1,0,3,2] row_mask:0xf bank_mask:0xf
	v_mul_f32_e32 v134, s5, v72
	v_mul_f32_e32 v135, s11, v72
	v_add_f32_dpp v87, v87, v87 quad_perm:[2,3,0,1] row_mask:0xf bank_mask:0xf
	v_fmac_f32_e32 v135, s9, v73
	v_mul_f32_e32 v92, s7, v72
	v_mov_b32_dpp v90, v87 row_newbcast:0 row_mask:0xf bank_mask:0xf
	v_add_f32_dpp v92, v87, v92 row_newbcast:4 row_mask:0xf bank_mask:0xf
	v_add_f32_dpp v91, v87, v134 row_newbcast:8 row_mask:0xf bank_mask:0xf
	v_pk_fma_f32 v[138:139], v[46:47], v[90:91], v[138:139] op_sel_hi:[1,0,1] neg_lo:[0,1,0] neg_hi:[0,1,0]
	v_fma_f32 v92, -v90, s6, v92
	v_pk_fma_f32 v[140:141], v[48:49], v[90:91], v[140:141] op_sel_hi:[1,0,1] neg_lo:[0,1,0] neg_hi:[0,1,0]
	v_add_f32_dpp v93, v87, v135 row_newbcast:12 row_mask:0xf bank_mask:0xf
	v_pk_fma_f32 v[138:139], v[54:55], v[92:93], v[138:139] op_sel_hi:[1,0,1] neg_lo:[0,1,0] neg_hi:[0,1,0]
	v_pk_fma_f32 v[140:141], v[56:57], v[92:93], v[140:141] op_sel_hi:[1,0,1] neg_lo:[0,1,0] neg_hi:[0,1,0]
	s_waitcnt lgkmcnt(0)
	s_load_dwordx8 s[28:35], s[96:97], 0x1c0
	v_pk_mul_f32 v[82:83], v[138:139], v[6:7]
	v_fma_f32 v91, -v90, s4, v91
	v_pk_mul_f32 v[84:85], v[138:139], v[10:11]
	v_fma_f32 v93, -v90, s10, v93
	v_pk_mul_f32 v[86:87], v[138:139], v[14:15]
	v_fma_f32 v93, -v92, s8, v93
	v_pk_mul_f32 v[88:89], v[138:139], v[18:19]
	ds_write2_b32 v166, v91, v93 offset0:96 offset1:112
	v_pk_fma_f32 v[82:83], v[140:141], v[8:9], v[82:83]
	ds_read_b128 v[42:45], v0 offset:45056
	v_pk_fma_f32 v[84:85], v[140:141], v[12:13], v[84:85]
	ds_read_b128 v[46:49], v0 offset:45312
	v_pk_fma_f32 v[86:87], v[140:141], v[16:17], v[86:87]
	ds_read_b128 v[50:53], v0 offset:45568
	v_pk_fma_f32 v[88:89], v[140:141], v[20:21], v[88:89]
	ds_read_b128 v[54:57], v0 offset:45824
	v_pk_mul_f32 v[138:139], v[138:139], v[22:23]
	ds_read_b128 v[58:61], v0 offset:46080
	v_pk_mul_f32 v[140:141], v[140:141], v[24:25]
	ds_read2st64_b32 v[72:73], v158 offset0:181 offset1:182
	v_add_f32_e32 v82, v82, v83
	v_add_f32_e32 v84, v84, v85
	v_add_f32_e32 v86, v86, v87
	v_add_f32_e32 v88, v88, v89
	ds_read_b128 v[6:9], v0 offset:44032
	ds_read_b128 v[10:13], v0 offset:44288
	ds_read_b128 v[14:17], v0 offset:44544
	ds_read_b128 v[18:21], v0 offset:44800
	v_add_f32_dpp v83, v82, v82 row_mirror row_mask:0xf bank_mask:0xf
	v_add_f32_dpp v83, v84, v84 row_mirror row_mask:0xf bank_mask:0xc
	v_add_f32_dpp v85, v86, v86 row_mirror row_mask:0xf bank_mask:0xf
	v_add_f32_dpp v85, v88, v88 row_mirror row_mask:0xf bank_mask:0xc
	v_add_f32_dpp v87, v83, v83 row_half_mirror row_mask:0xf bank_mask:0xf
	v_pk_fma_f32 v[138:139], v[30:31], v[62:63], v[138:139] op_sel_hi:[1,0,1]
	v_pk_fma_f32 v[140:141], v[32:33], v[62:63], v[140:141] op_sel_hi:[1,0,1]
	v_add_f32_dpp v87, v85, v85 row_half_mirror row_mask:0xf bank_mask:0xa
	v_pk_fma_f32 v[138:139], v[38:39], v[62:63], v[138:139] op_sel:[0,1,0] op_sel_hi:[1,1,1]
	v_pk_fma_f32 v[140:141], v[40:41], v[62:63], v[140:141] op_sel:[0,1,0] op_sel_hi:[1,1,1]
	v_add_f32_dpp v87, v87, v87 quad_perm:[1,0,3,2] row_mask:0xf bank_mask:0xf
	v_mul_f32_e32 v134, s77, v62
	v_mul_f32_e32 v135, s83, v62
	v_add_f32_dpp v87, v87, v87 quad_perm:[2,3,0,1] row_mask:0xf bank_mask:0xf
	v_fmac_f32_e32 v135, s81, v63
	v_mul_f32_e32 v92, s79, v62
	v_mov_b32_dpp v90, v87 row_newbcast:0 row_mask:0xf bank_mask:0xf
	v_add_f32_dpp v92, v87, v92 row_newbcast:4 row_mask:0xf bank_mask:0xf
	v_add_f32_dpp v91, v87, v134 row_newbcast:8 row_mask:0xf bank_mask:0xf
	v_pk_fma_f32 v[138:139], v[26:27], v[90:91], v[138:139] op_sel_hi:[1,0,1] neg_lo:[0,1,0] neg_hi:[0,1,0]
	v_fma_f32 v92, -v90, s78, v92
	v_pk_fma_f32 v[140:141], v[28:29], v[90:91], v[140:141] op_sel_hi:[1,0,1] neg_lo:[0,1,0] neg_hi:[0,1,0]
	v_add_f32_dpp v93, v87, v135 row_newbcast:12 row_mask:0xf bank_mask:0xf
	v_pk_fma_f32 v[138:139], v[34:35], v[92:93], v[138:139] op_sel_hi:[1,0,1] neg_lo:[0,1,0] neg_hi:[0,1,0]
	v_pk_fma_f32 v[140:141], v[36:37], v[92:93], v[140:141] op_sel_hi:[1,0,1] neg_lo:[0,1,0] neg_hi:[0,1,0]
	s_waitcnt lgkmcnt(0)
	s_load_dwordx8 s[4:11], s[96:97], 0x1e0
	v_pk_mul_f32 v[82:83], v[138:139], v[6:7]
	v_fma_f32 v91, -v90, s76, v91
	v_pk_mul_f32 v[84:85], v[138:139], v[10:11]
	v_fma_f32 v93, -v90, s82, v93
	v_pk_mul_f32 v[86:87], v[138:139], v[14:15]
	v_fma_f32 v93, -v92, s80, v93
	v_pk_mul_f32 v[88:89], v[138:139], v[18:19]
	ds_write2_b32 v166, v91, v93 offset0:128 offset1:144
	v_pk_fma_f32 v[82:83], v[140:141], v[8:9], v[82:83]
	ds_read_b128 v[22:25], v0 offset:48128
	v_pk_fma_f32 v[84:85], v[140:141], v[12:13], v[84:85]
	ds_read_b128 v[26:29], v0 offset:48384
	v_pk_fma_f32 v[86:87], v[140:141], v[16:17], v[86:87]
	ds_read_b128 v[30:33], v0 offset:48640
	v_pk_fma_f32 v[88:89], v[140:141], v[20:21], v[88:89]
	ds_read_b128 v[34:37], v0 offset:48896
	v_pk_mul_f32 v[138:139], v[138:139], v[42:43]
	ds_read_b128 v[38:41], v0 offset:49152
	v_pk_mul_f32 v[140:141], v[140:141], v[44:45]
	ds_read2st64_b32 v[62:63], v158 offset0:193 offset1:194
	v_add_f32_e32 v82, v82, v83
	v_add_f32_e32 v84, v84, v85
	v_add_f32_e32 v86, v86, v87
	v_add_f32_e32 v88, v88, v89
	ds_read_b128 v[6:9], v0 offset:47104
	ds_read_b128 v[10:13], v0 offset:47360
	ds_read_b128 v[14:17], v0 offset:47616
	ds_read_b128 v[18:21], v0 offset:47872
	v_add_f32_dpp v83, v82, v82 row_mirror row_mask:0xf bank_mask:0xf
	v_add_f32_dpp v83, v84, v84 row_mirror row_mask:0xf bank_mask:0xc
	v_add_f32_dpp v85, v86, v86 row_mirror row_mask:0xf bank_mask:0xf
	v_add_f32_dpp v85, v88, v88 row_mirror row_mask:0xf bank_mask:0xc
	v_add_f32_dpp v87, v83, v83 row_half_mirror row_mask:0xf bank_mask:0xf
	v_pk_fma_f32 v[138:139], v[50:51], v[72:73], v[138:139] op_sel_hi:[1,0,1]
	v_pk_fma_f32 v[140:141], v[52:53], v[72:73], v[140:141] op_sel_hi:[1,0,1]
	v_add_f32_dpp v87, v85, v85 row_half_mirror row_mask:0xf bank_mask:0xa
	v_pk_fma_f32 v[138:139], v[58:59], v[72:73], v[138:139] op_sel:[0,1,0] op_sel_hi:[1,1,1]
	v_pk_fma_f32 v[140:141], v[60:61], v[72:73], v[140:141] op_sel:[0,1,0] op_sel_hi:[1,1,1]
	v_add_f32_dpp v87, v87, v87 quad_perm:[1,0,3,2] row_mask:0xf bank_mask:0xf
	v_mul_f32_e32 v134, s89, v72
	v_mul_f32_e32 v135, s95, v72
	v_add_f32_dpp v87, v87, v87 quad_perm:[2,3,0,1] row_mask:0xf bank_mask:0xf
	v_fmac_f32_e32 v135, s93, v73
	v_mul_f32_e32 v92, s91, v72
	v_mov_b32_dpp v90, v87 row_newbcast:0 row_mask:0xf bank_mask:0xf
	v_add_f32_dpp v92, v87, v92 row_newbcast:4 row_mask:0xf bank_mask:0xf
	v_add_f32_dpp v91, v87, v134 row_newbcast:8 row_mask:0xf bank_mask:0xf
	v_pk_fma_f32 v[138:139], v[46:47], v[90:91], v[138:139] op_sel_hi:[1,0,1] neg_lo:[0,1,0] neg_hi:[0,1,0]
	v_fma_f32 v92, -v90, s90, v92
	v_pk_fma_f32 v[140:141], v[48:49], v[90:91], v[140:141] op_sel_hi:[1,0,1] neg_lo:[0,1,0] neg_hi:[0,1,0]
	v_add_f32_dpp v93, v87, v135 row_newbcast:12 row_mask:0xf bank_mask:0xf
	v_pk_fma_f32 v[138:139], v[54:55], v[92:93], v[138:139] op_sel_hi:[1,0,1] neg_lo:[0,1,0] neg_hi:[0,1,0]
	v_pk_fma_f32 v[140:141], v[56:57], v[92:93], v[140:141] op_sel_hi:[1,0,1] neg_lo:[0,1,0] neg_hi:[0,1,0]
	s_waitcnt lgkmcnt(0)
	s_add_i32 m0, s41, 1
	s_min_u32 m0, m0, 0x1ff
	s_lshl_b32 m0, m0, 9
	s_add_u32 s96, s100, m0
	s_addc_u32 s97, s101, 0
	s_load_dwordx8 s[76:83], s[96:97], 0x0
	v_pk_mul_f32 v[82:83], v[138:139], v[6:7]
	v_fma_f32 v91, -v90, s88, v91
	v_pk_mul_f32 v[84:85], v[138:139], v[10:11]
	v_fma_f32 v93, -v90, s94, v93
	v_pk_mul_f32 v[86:87], v[138:139], v[14:15]
	v_fma_f32 v93, -v92, s92, v93
	v_pk_mul_f32 v[88:89], v[138:139], v[18:19]
	ds_write2_b32 v166, v91, v93 offset0:160 offset1:176
	v_pk_fma_f32 v[82:83], v[140:141], v[8:9], v[82:83]
	ds_read_b128 v[42:45], v0 offset:51200
	v_pk_fma_f32 v[84:85], v[140:141], v[12:13], v[84:85]
	ds_read_b128 v[46:49], v0 offset:51456
	v_pk_fma_f32 v[86:87], v[140:141], v[16:17], v[86:87]
	ds_read_b128 v[50:53], v0 offset:51712
	v_pk_fma_f32 v[88:89], v[140:141], v[20:21], v[88:89]
	ds_read_b128 v[54:57], v0 offset:51968
	v_pk_mul_f32 v[138:139], v[138:139], v[22:23]
	ds_read_b128 v[58:61], v0 offset:52224
	v_pk_mul_f32 v[140:141], v[140:141], v[24:25]
	ds_read2st64_b32 v[72:73], v158 offset0:205 offset1:206
	v_add_f32_e32 v82, v82, v83
	v_add_f32_e32 v84, v84, v85
	v_add_f32_e32 v86, v86, v87
	v_add_f32_e32 v88, v88, v89
	ds_read_b128 v[6:9], v0 offset:50176
	ds_read_b128 v[10:13], v0 offset:50432
	ds_read_b128 v[14:17], v0 offset:50688
	ds_read_b128 v[18:21], v0 offset:50944
	v_add_f32_dpp v83, v82, v82 row_mirror row_mask:0xf bank_mask:0xf
	v_add_f32_dpp v83, v84, v84 row_mirror row_mask:0xf bank_mask:0xc
	v_add_f32_dpp v85, v86, v86 row_mirror row_mask:0xf bank_mask:0xf
	v_add_f32_dpp v85, v88, v88 row_mirror row_mask:0xf bank_mask:0xc
	v_add_f32_dpp v87, v83, v83 row_half_mirror row_mask:0xf bank_mask:0xf
	v_pk_fma_f32 v[138:139], v[30:31], v[62:63], v[138:139] op_sel_hi:[1,0,1]
	v_pk_fma_f32 v[140:141], v[32:33], v[62:63], v[140:141] op_sel_hi:[1,0,1]
	v_add_f32_dpp v87, v85, v85 row_half_mirror row_mask:0xf bank_mask:0xa
	v_pk_fma_f32 v[138:139], v[38:39], v[62:63], v[138:139] op_sel:[0,1,0] op_sel_hi:[1,1,1]
	v_pk_fma_f32 v[140:141], v[40:41], v[62:63], v[140:141] op_sel:[0,1,0] op_sel_hi:[1,1,1]
	v_add_f32_dpp v87, v87, v87 quad_perm:[1,0,3,2] row_mask:0xf bank_mask:0xf
	v_mul_f32_e32 v134, s29, v62
	v_mul_f32_e32 v135, s35, v62
	v_add_f32_dpp v87, v87, v87 quad_perm:[2,3,0,1] row_mask:0xf bank_mask:0xf
	v_fmac_f32_e32 v135, s33, v63
	v_mul_f32_e32 v92, s31, v62
	v_mov_b32_dpp v90, v87 row_newbcast:0 row_mask:0xf bank_mask:0xf
	v_add_f32_dpp v92, v87, v92 row_newbcast:4 row_mask:0xf bank_mask:0xf
	v_add_f32_dpp v91, v87, v134 row_newbcast:8 row_mask:0xf bank_mask:0xf
	v_pk_fma_f32 v[138:139], v[26:27], v[90:91], v[138:139] op_sel_hi:[1,0,1] neg_lo:[0,1,0] neg_hi:[0,1,0]
	v_fma_f32 v92, -v90, s30, v92
	v_pk_fma_f32 v[140:141], v[28:29], v[90:91], v[140:141] op_sel_hi:[1,0,1] neg_lo:[0,1,0] neg_hi:[0,1,0]
	v_add_f32_dpp v93, v87, v135 row_newbcast:12 row_mask:0xf bank_mask:0xf
	v_pk_fma_f32 v[138:139], v[34:35], v[92:93], v[138:139] op_sel_hi:[1,0,1] neg_lo:[0,1,0] neg_hi:[0,1,0]
	v_pk_fma_f32 v[140:141], v[36:37], v[92:93], v[140:141] op_sel_hi:[1,0,1] neg_lo:[0,1,0] neg_hi:[0,1,0]
	s_waitcnt lgkmcnt(0)
	s_load_dwordx8 s[88:95], s[96:97], 0x20
	v_pk_mul_f32 v[82:83], v[138:139], v[6:7]
	v_fma_f32 v91, -v90, s28, v91
	v_pk_mul_f32 v[84:85], v[138:139], v[10:11]
	v_fma_f32 v93, -v90, s34, v93
	v_pk_mul_f32 v[86:87], v[138:139], v[14:15]
	v_fma_f32 v93, -v92, s32, v93
	v_pk_mul_f32 v[88:89], v[138:139], v[18:19]
	ds_write2_b32 v166, v91, v93 offset0:192 offset1:208
	v_pk_fma_f32 v[82:83], v[140:141], v[8:9], v[82:83]
	v_pk_fma_f32 v[84:85], v[140:141], v[12:13], v[84:85]
	v_pk_fma_f32 v[86:87], v[140:141], v[16:17], v[86:87]
	v_pk_fma_f32 v[88:89], v[140:141], v[20:21], v[88:89]
	v_pk_mul_f32 v[138:139], v[138:139], v[42:43]
	v_pk_mul_f32 v[140:141], v[140:141], v[44:45]
	v_add_f32_e32 v82, v82, v83
	v_add_f32_e32 v84, v84, v85
	v_add_f32_e32 v86, v86, v87
	v_add_f32_e32 v88, v88, v89
	v_add_f32_dpp v83, v82, v82 row_mirror row_mask:0xf bank_mask:0xf
	v_add_f32_dpp v83, v84, v84 row_mirror row_mask:0xf bank_mask:0xc
	v_add_f32_dpp v85, v86, v86 row_mirror row_mask:0xf bank_mask:0xf
	v_add_f32_dpp v85, v88, v88 row_mirror row_mask:0xf bank_mask:0xc
	v_add_f32_dpp v87, v83, v83 row_half_mirror row_mask:0xf bank_mask:0xf
	v_pk_fma_f32 v[138:139], v[50:51], v[72:73], v[138:139] op_sel_hi:[1,0,1]
	v_pk_fma_f32 v[140:141], v[52:53], v[72:73], v[140:141] op_sel_hi:[1,0,1]
	v_add_f32_dpp v87, v85, v85 row_half_mirror row_mask:0xf bank_mask:0xa
	v_pk_fma_f32 v[138:139], v[58:59], v[72:73], v[138:139] op_sel:[0,1,0] op_sel_hi:[1,1,1]
	v_pk_fma_f32 v[140:141], v[60:61], v[72:73], v[140:141] op_sel:[0,1,0] op_sel_hi:[1,1,1]
	v_add_f32_dpp v87, v87, v87 quad_perm:[1,0,3,2] row_mask:0xf bank_mask:0xf
	v_mul_f32_e32 v134, s5, v72
	v_mul_f32_e32 v135, s11, v72
	v_add_f32_dpp v87, v87, v87 quad_perm:[2,3,0,1] row_mask:0xf bank_mask:0xf
	v_fmac_f32_e32 v135, s9, v73
	v_mul_f32_e32 v92, s7, v72
	v_mov_b32_dpp v90, v87 row_newbcast:0 row_mask:0xf bank_mask:0xf
	v_add_f32_dpp v92, v87, v92 row_newbcast:4 row_mask:0xf bank_mask:0xf
	v_add_f32_dpp v91, v87, v134 row_newbcast:8 row_mask:0xf bank_mask:0xf
	v_pk_fma_f32 v[138:139], v[46:47], v[90:91], v[138:139] op_sel_hi:[1,0,1] neg_lo:[0,1,0] neg_hi:[0,1,0]
	v_fma_f32 v92, -v90, s6, v92
	v_pk_fma_f32 v[140:141], v[48:49], v[90:91], v[140:141] op_sel_hi:[1,0,1] neg_lo:[0,1,0] neg_hi:[0,1,0]
	v_add_f32_dpp v93, v87, v135 row_newbcast:12 row_mask:0xf bank_mask:0xf
	v_pk_fma_f32 v[138:139], v[54:55], v[92:93], v[138:139] op_sel_hi:[1,0,1] neg_lo:[0,1,0] neg_hi:[0,1,0]
	v_pk_fma_f32 v[140:141], v[56:57], v[92:93], v[140:141] op_sel_hi:[1,0,1] neg_lo:[0,1,0] neg_hi:[0,1,0]
	v_fma_f32 v91, -v90, s4, v91
	v_fma_f32 v93, -v90, s10, v93
	v_fma_f32 v93, -v92, s8, v93
	ds_write2_b32 v166, v91, v93 offset0:224 offset1:240
